# +E15 gated-delta forward substitution rewritten: wave-uniform ds_read_b128 coefficients + v_pk_fma_f32 on the x register pairs (1216 VALU + 528 LDS reads instead of 4032 VALU)
# speedup vs baseline: 1.0206x; 1.0013x over previous
; __device__ __forceinline__ void gd_prep_item(CArgs* a, LAS unsigned char* lds, int l, int item) {
;     ...
;         float nrow[64];
; #pragma unroll
;         for (int t = 1; t < 64; ++t) nrow[t] = NM[t * 64 + lane];
; #pragma unroll
;         for (int t = 1; t < 64; ++t) { float s0 = 0.f, s1 = 0.f;
; #pragma unroll
;             for (int sI = 0; sI < t; ++sI) { const float cf = __builtin_bit_cast(float, __builtin_amdgcn_readlane(__builtin_bit_cast(int, nrow[t]), sI)); if (sI & 1) s1 += cf * x[sI]; else s0 += cf * x[sI]; }
;             x[t] -= s0 + s1; }
.LBB0_989:
	s_or_b64 exec, exec, s[10:11]
	ds_read_b128 v[84:87], v116 offset:256
	ds_read_b128 v[88:91], v116 offset:512
	ds_read_b128 v[92:95], v116 offset:768
	ds_read_b128 v[96:99], v116 offset:1024
	ds_read_b128 v[100:103], v116 offset:1280
	ds_read_b128 v[104:107], v116 offset:1296
	ds_read_b128 v[108:111], v116 offset:1536
	ds_read_b128 v[112:115], v116 offset:1552
	s_waitcnt lgkmcnt(7)
	v_pk_mul_f32 v[128:129], v[84:85], v[4:5] op_sel:[0,1] op_sel_hi:[1,0]
	ds_read_b128 v[84:87], v116 offset:1792
	v_add_f32_e32 v133, v128, v129
	v_sub_f32_e32 v4, v4, v133
	s_waitcnt lgkmcnt(7)
	v_pk_mul_f32 v[124:125], v[88:89], v[4:5] op_sel:[0,1] op_sel_hi:[1,0]
	ds_read_b128 v[88:91], v116 offset:1808
	s_waitcnt lgkmcnt(7)
	v_pk_mul_f32 v[128:129], v[92:93], v[4:5] op_sel:[0,1] op_sel_hi:[1,0]
	v_add_f32_e32 v132, v124, v125
	v_sub_f32_e32 v70, v70, v132
	v_pk_mul_f32 v[130:131], v[94:95], v[70:71]
	ds_read_b128 v[92:95], v116 offset:2048
	s_waitcnt lgkmcnt(7)
	v_pk_mul_f32 v[124:125], v[96:97], v[4:5] op_sel:[0,1] op_sel_hi:[1,0]
	v_pk_add_f32 v[128:129], v[128:129], v[130:131]
	v_add_f32_e32 v133, v128, v129
	v_sub_f32_e32 v71, v71, v133
	v_pk_mul_f32 v[126:127], v[98:99], v[70:71]
	ds_read_b128 v[96:99], v116 offset:2064
	s_waitcnt lgkmcnt(7)
	v_pk_mul_f32 v[128:129], v[100:101], v[4:5] op_sel:[0,1] op_sel_hi:[1,0]
	v_pk_mul_f32 v[130:131], v[102:103], v[70:71]
	ds_read_b128 v[100:103], v116 offset:2304
	v_pk_add_f32 v[124:125], v[124:125], v[126:127]
	v_add_f32_e32 v132, v124, v125
	v_sub_f32_e32 v74, v74, v132
	s_waitcnt lgkmcnt(7)
	v_pk_fma_f32 v[128:129], v[104:105], v[74:75], v[128:129]
	ds_read_b128 v[104:107], v116 offset:2320
	s_waitcnt lgkmcnt(7)
	v_pk_mul_f32 v[124:125], v[108:109], v[4:5] op_sel:[0,1] op_sel_hi:[1,0]
	v_pk_mul_f32 v[126:127], v[110:111], v[70:71]
	ds_read_b128 v[108:111], v116 offset:2336
	v_pk_add_f32 v[128:129], v[128:129], v[130:131]
	v_add_f32_e32 v133, v128, v129
	v_sub_f32_e32 v75, v75, v133
	s_waitcnt lgkmcnt(7)
	v_pk_fma_f32 v[124:125], v[112:113], v[74:75], v[124:125]
	ds_read_b128 v[112:115], v116 offset:2560
	s_waitcnt lgkmcnt(7)
	v_pk_mul_f32 v[128:129], v[84:85], v[4:5] op_sel:[0,1] op_sel_hi:[1,0]
	v_pk_mul_f32 v[130:131], v[86:87], v[70:71]
	ds_read_b128 v[84:87], v116 offset:2576
	s_waitcnt lgkmcnt(7)
	v_pk_fma_f32 v[128:129], v[88:89], v[74:75], v[128:129]
	v_pk_add_f32 v[124:125], v[124:125], v[126:127]
	v_add_f32_e32 v132, v124, v125
	v_sub_f32_e32 v80, v80, v132
	v_pk_fma_f32 v[130:131], v[90:91], v[80:81], v[130:131]
	ds_read_b128 v[88:91], v116 offset:2592
	s_waitcnt lgkmcnt(7)
	v_pk_mul_f32 v[124:125], v[92:93], v[4:5] op_sel:[0,1] op_sel_hi:[1,0]
	v_pk_mul_f32 v[126:127], v[94:95], v[70:71]
	ds_read_b128 v[92:95], v116 offset:2816
	s_waitcnt lgkmcnt(7)
	v_pk_fma_f32 v[124:125], v[96:97], v[74:75], v[124:125]
	v_pk_add_f32 v[128:129], v[128:129], v[130:131]
	v_add_f32_e32 v133, v128, v129
	v_sub_f32_e32 v81, v81, v133
	v_pk_fma_f32 v[126:127], v[98:99], v[80:81], v[126:127]
	ds_read_b128 v[96:99], v116 offset:2832
	s_waitcnt lgkmcnt(7)
	v_pk_mul_f32 v[128:129], v[100:101], v[4:5] op_sel:[0,1] op_sel_hi:[1,0]
	v_pk_mul_f32 v[130:131], v[102:103], v[70:71]
	ds_read_b128 v[100:103], v116 offset:2848
	s_waitcnt lgkmcnt(7)
	v_pk_fma_f32 v[128:129], v[104:105], v[74:75], v[128:129]
	v_pk_fma_f32 v[130:131], v[106:107], v[80:81], v[130:131]
	ds_read_b128 v[104:107], v116 offset:3072
	v_pk_add_f32 v[124:125], v[124:125], v[126:127]
	v_add_f32_e32 v132, v124, v125
	v_sub_f32_e32 v78, v78, v132
	s_waitcnt lgkmcnt(7)
	v_pk_fma_f32 v[128:129], v[108:109], v[78:79], v[128:129]
	ds_read_b128 v[108:111], v116 offset:3088
	s_waitcnt lgkmcnt(7)
	v_pk_mul_f32 v[124:125], v[112:113], v[4:5] op_sel:[0,1] op_sel_hi:[1,0]
	v_pk_mul_f32 v[126:127], v[114:115], v[70:71]
	ds_read_b128 v[112:115], v116 offset:3104
	s_waitcnt lgkmcnt(7)
	v_pk_fma_f32 v[124:125], v[84:85], v[74:75], v[124:125]
	v_pk_fma_f32 v[126:127], v[86:87], v[80:81], v[126:127]
	ds_read_b128 v[84:87], v116 offset:3328
	v_pk_add_f32 v[128:129], v[128:129], v[130:131]
	v_add_f32_e32 v133, v128, v129
	v_sub_f32_e32 v79, v79, v133
	s_waitcnt lgkmcnt(7)
	v_pk_fma_f32 v[124:125], v[88:89], v[78:79], v[124:125]
	ds_read_b128 v[88:91], v116 offset:3344
	s_waitcnt lgkmcnt(7)
	v_pk_mul_f32 v[128:129], v[92:93], v[4:5] op_sel:[0,1] op_sel_hi:[1,0]
	v_pk_mul_f32 v[130:131], v[94:95], v[70:71]
	ds_read_b128 v[92:95], v116 offset:3360
	s_waitcnt lgkmcnt(7)
	v_pk_fma_f32 v[128:129], v[96:97], v[74:75], v[128:129]
	v_pk_fma_f32 v[130:131], v[98:99], v[80:81], v[130:131]
	ds_read_b128 v[96:99], v116 offset:3376
	s_waitcnt lgkmcnt(7)
	v_pk_fma_f32 v[128:129], v[100:101], v[78:79], v[128:129]
	v_pk_add_f32 v[124:125], v[124:125], v[126:127]
	v_add_f32_e32 v132, v124, v125
	v_sub_f32_e32 v76, v76, v132
	v_pk_fma_f32 v[130:131], v[102:103], v[76:77], v[130:131]
	ds_read_b128 v[100:103], v116 offset:3584
	s_waitcnt lgkmcnt(7)
	v_pk_mul_f32 v[124:125], v[104:105], v[4:5] op_sel:[0,1] op_sel_hi:[1,0]
	v_pk_mul_f32 v[126:127], v[106:107], v[70:71]
	ds_read_b128 v[104:107], v116 offset:3600
	s_waitcnt lgkmcnt(7)
	v_pk_fma_f32 v[124:125], v[108:109], v[74:75], v[124:125]
	v_pk_fma_f32 v[126:127], v[110:111], v[80:81], v[126:127]
	ds_read_b128 v[108:111], v116 offset:3616
	s_waitcnt lgkmcnt(7)
	v_pk_fma_f32 v[124:125], v[112:113], v[78:79], v[124:125]
	v_pk_add_f32 v[128:129], v[128:129], v[130:131]
	v_add_f32_e32 v133, v128, v129
	v_sub_f32_e32 v77, v77, v133
	v_pk_fma_f32 v[126:127], v[114:115], v[76:77], v[126:127]
	ds_read_b128 v[112:115], v116 offset:3632
	s_waitcnt lgkmcnt(7)
; __device__ __forceinline__ void gd_prep_item(CArgs* a, LAS unsigned char* lds, int l, int item) {
;     ...
;         for (int t = 1; t < 64; ++t) { float s0 = 0.f, s1 = 0.f;
; #pragma unroll
;             for (int sI = 0; sI < t; ++sI) { const float cf = __builtin_bit_cast(float, __builtin_amdgcn_readlane(__builtin_bit_cast(int, nrow[t]), sI)); if (sI & 1) s1 += cf * x[sI]; else s0 += cf * x[sI]; }
;             x[t] -= s0 + s1; }
	v_pk_mul_f32 v[128:129], v[84:85], v[4:5] op_sel:[0,1] op_sel_hi:[1,0]
	v_pk_mul_f32 v[130:131], v[86:87], v[70:71]
	ds_read_b128 v[84:87], v116 offset:3840
	s_waitcnt lgkmcnt(7)
	v_pk_fma_f32 v[128:129], v[88:89], v[74:75], v[128:129]
	v_pk_fma_f32 v[130:131], v[90:91], v[80:81], v[130:131]
	ds_read_b128 v[88:91], v116 offset:3856
	s_waitcnt lgkmcnt(7)
	v_pk_fma_f32 v[128:129], v[92:93], v[78:79], v[128:129]
	v_pk_fma_f32 v[130:131], v[94:95], v[76:77], v[130:131]
	ds_read_b128 v[92:95], v116 offset:3872
	v_pk_add_f32 v[124:125], v[124:125], v[126:127]
	v_add_f32_e32 v132, v124, v125
	v_sub_f32_e32 v72, v72, v132
	s_waitcnt lgkmcnt(7)
	v_pk_fma_f32 v[128:129], v[96:97], v[72:73], v[128:129]
	ds_read_b128 v[96:99], v116 offset:3888
	s_waitcnt lgkmcnt(7)
	v_pk_mul_f32 v[124:125], v[100:101], v[4:5] op_sel:[0,1] op_sel_hi:[1,0]
	v_pk_mul_f32 v[126:127], v[102:103], v[70:71]
	ds_read_b128 v[100:103], v116 offset:4096
	s_waitcnt lgkmcnt(7)
	v_pk_fma_f32 v[124:125], v[104:105], v[74:75], v[124:125]
	v_pk_fma_f32 v[126:127], v[106:107], v[80:81], v[126:127]
	ds_read_b128 v[104:107], v116 offset:4112
	s_waitcnt lgkmcnt(7)
	v_pk_fma_f32 v[124:125], v[108:109], v[78:79], v[124:125]
	v_pk_fma_f32 v[126:127], v[110:111], v[76:77], v[126:127]
	ds_read_b128 v[108:111], v116 offset:4128
	v_pk_add_f32 v[128:129], v[128:129], v[130:131]
	v_add_f32_e32 v133, v128, v129
	v_sub_f32_e32 v73, v73, v133
	s_waitcnt lgkmcnt(7)
	v_pk_fma_f32 v[124:125], v[112:113], v[72:73], v[124:125]
	ds_read_b128 v[112:115], v116 offset:4144
	s_waitcnt lgkmcnt(7)
	v_pk_mul_f32 v[128:129], v[84:85], v[4:5] op_sel:[0,1] op_sel_hi:[1,0]
	v_pk_mul_f32 v[130:131], v[86:87], v[70:71]
	ds_read_b128 v[84:87], v116 offset:4352
	s_waitcnt lgkmcnt(7)
	v_pk_fma_f32 v[128:129], v[88:89], v[74:75], v[128:129]
	v_pk_fma_f32 v[130:131], v[90:91], v[80:81], v[130:131]
	ds_read_b128 v[88:91], v116 offset:4368
	s_waitcnt lgkmcnt(7)
	v_pk_fma_f32 v[128:129], v[92:93], v[78:79], v[128:129]
	v_pk_fma_f32 v[130:131], v[94:95], v[76:77], v[130:131]
	ds_read_b128 v[92:95], v116 offset:4384
	s_waitcnt lgkmcnt(7)
	v_pk_fma_f32 v[128:129], v[96:97], v[72:73], v[128:129]
	v_pk_add_f32 v[124:125], v[124:125], v[126:127]
	v_add_f32_e32 v132, v124, v125
	v_sub_f32_e32 v66, v66, v132
	v_pk_fma_f32 v[130:131], v[98:99], v[66:67], v[130:131]
	ds_read_b128 v[96:99], v116 offset:4400
	s_waitcnt lgkmcnt(7)
	v_pk_mul_f32 v[124:125], v[100:101], v[4:5] op_sel:[0,1] op_sel_hi:[1,0]
	v_pk_mul_f32 v[126:127], v[102:103], v[70:71]
	ds_read_b128 v[100:103], v116 offset:4416
	s_waitcnt lgkmcnt(7)
	v_pk_fma_f32 v[124:125], v[104:105], v[74:75], v[124:125]
	v_pk_fma_f32 v[126:127], v[106:107], v[80:81], v[126:127]
	ds_read_b128 v[104:107], v116 offset:4608
	s_waitcnt lgkmcnt(7)
	v_pk_fma_f32 v[124:125], v[108:109], v[78:79], v[124:125]
	v_pk_fma_f32 v[126:127], v[110:111], v[76:77], v[126:127]
	ds_read_b128 v[108:111], v116 offset:4624
	s_waitcnt lgkmcnt(7)
	v_pk_fma_f32 v[124:125], v[112:113], v[72:73], v[124:125]
	v_pk_add_f32 v[128:129], v[128:129], v[130:131]
	v_add_f32_e32 v133, v128, v129
	v_sub_f32_e32 v67, v67, v133
	v_pk_fma_f32 v[126:127], v[114:115], v[66:67], v[126:127]
	ds_read_b128 v[112:115], v116 offset:4640
	s_waitcnt lgkmcnt(7)
	v_pk_mul_f32 v[128:129], v[84:85], v[4:5] op_sel:[0,1] op_sel_hi:[1,0]
	v_pk_mul_f32 v[130:131], v[86:87], v[70:71]
	ds_read_b128 v[84:87], v116 offset:4656
	s_waitcnt lgkmcnt(7)
	v_pk_fma_f32 v[128:129], v[88:89], v[74:75], v[128:129]
	v_pk_fma_f32 v[130:131], v[90:91], v[80:81], v[130:131]
	ds_read_b128 v[88:91], v116 offset:4672
	s_waitcnt lgkmcnt(7)
	v_pk_fma_f32 v[128:129], v[92:93], v[78:79], v[128:129]
	v_pk_fma_f32 v[130:131], v[94:95], v[76:77], v[130:131]
	ds_read_b128 v[92:95], v116 offset:4864
	s_waitcnt lgkmcnt(7)
	v_pk_fma_f32 v[128:129], v[96:97], v[72:73], v[128:129]
	v_pk_fma_f32 v[130:131], v[98:99], v[66:67], v[130:131]
	ds_read_b128 v[96:99], v116 offset:4880
	v_pk_add_f32 v[124:125], v[124:125], v[126:127]
	v_add_f32_e32 v132, v124, v125
	v_sub_f32_e32 v64, v64, v132
	s_waitcnt lgkmcnt(7)
	v_pk_fma_f32 v[128:129], v[100:101], v[64:65], v[128:129]
	ds_read_b128 v[100:103], v116 offset:4896
	s_waitcnt lgkmcnt(7)
	v_pk_mul_f32 v[124:125], v[104:105], v[4:5] op_sel:[0,1] op_sel_hi:[1,0]
	v_pk_mul_f32 v[126:127], v[106:107], v[70:71]
	ds_read_b128 v[104:107], v116 offset:4912
	s_waitcnt lgkmcnt(7)
	v_pk_fma_f32 v[124:125], v[108:109], v[74:75], v[124:125]
	v_pk_fma_f32 v[126:127], v[110:111], v[80:81], v[126:127]
	ds_read_b128 v[108:111], v116 offset:4928
	s_waitcnt lgkmcnt(7)
	v_pk_fma_f32 v[124:125], v[112:113], v[78:79], v[124:125]
	v_pk_fma_f32 v[126:127], v[114:115], v[76:77], v[126:127]
	ds_read_b128 v[112:115], v116 offset:5120
	s_waitcnt lgkmcnt(7)
	v_pk_fma_f32 v[124:125], v[84:85], v[72:73], v[124:125]
	v_pk_fma_f32 v[126:127], v[86:87], v[66:67], v[126:127]
	ds_read_b128 v[84:87], v116 offset:5136
	v_pk_add_f32 v[128:129], v[128:129], v[130:131]
	v_add_f32_e32 v133, v128, v129
	v_sub_f32_e32 v65, v65, v133
	s_waitcnt lgkmcnt(7)
	v_pk_fma_f32 v[124:125], v[88:89], v[64:65], v[124:125]
	ds_read_b128 v[88:91], v116 offset:5152
	s_waitcnt lgkmcnt(7)
	v_pk_mul_f32 v[128:129], v[92:93], v[4:5] op_sel:[0,1] op_sel_hi:[1,0]
	v_pk_mul_f32 v[130:131], v[94:95], v[70:71]
	ds_read_b128 v[92:95], v116 offset:5168
	s_waitcnt lgkmcnt(7)
	v_pk_fma_f32 v[128:129], v[96:97], v[74:75], v[128:129]
	v_pk_fma_f32 v[130:131], v[98:99], v[80:81], v[130:131]
	ds_read_b128 v[96:99], v116 offset:5184
	s_waitcnt lgkmcnt(7)
	v_pk_fma_f32 v[128:129], v[100:101], v[78:79], v[128:129]
	v_pk_fma_f32 v[130:131], v[102:103], v[76:77], v[130:131]
	ds_read_b128 v[100:103], v116 offset:5376
	s_waitcnt lgkmcnt(7)
; __device__ __forceinline__ void gd_prep_item(CArgs* a, LAS unsigned char* lds, int l, int item) {
;     ...
;         for (int t = 1; t < 64; ++t) nrow[t] = NM[t * 64 + lane];
; #pragma unroll
;         for (int t = 1; t < 64; ++t) { float s0 = 0.f, s1 = 0.f;
; #pragma unroll
;             for (int sI = 0; sI < t; ++sI) { const float cf = __builtin_bit_cast(float, __builtin_amdgcn_readlane(__builtin_bit_cast(int, nrow[t]), sI)); if (sI & 1) s1 += cf * x[sI]; else s0 += cf * x[sI]; }
;             x[t] -= s0 + s1; }
	v_pk_fma_f32 v[128:129], v[104:105], v[72:73], v[128:129]
	v_pk_fma_f32 v[130:131], v[106:107], v[66:67], v[130:131]
	ds_read_b128 v[104:107], v116 offset:5392
	s_waitcnt lgkmcnt(7)
	v_pk_fma_f32 v[128:129], v[108:109], v[64:65], v[128:129]
	v_pk_add_f32 v[124:125], v[124:125], v[126:127]
	v_add_f32_e32 v132, v124, v125
	v_sub_f32_e32 v62, v62, v132
	v_pk_fma_f32 v[130:131], v[110:111], v[62:63], v[130:131]
	ds_read_b128 v[108:111], v116 offset:5408
	s_waitcnt lgkmcnt(7)
	v_pk_mul_f32 v[124:125], v[112:113], v[4:5] op_sel:[0,1] op_sel_hi:[1,0]
	v_pk_mul_f32 v[126:127], v[114:115], v[70:71]
	ds_read_b128 v[112:115], v116 offset:5424
	s_waitcnt lgkmcnt(7)
	v_pk_fma_f32 v[124:125], v[84:85], v[74:75], v[124:125]
	v_pk_fma_f32 v[126:127], v[86:87], v[80:81], v[126:127]
	ds_read_b128 v[84:87], v116 offset:5440
	s_waitcnt lgkmcnt(7)
	v_pk_fma_f32 v[124:125], v[88:89], v[78:79], v[124:125]
	v_pk_fma_f32 v[126:127], v[90:91], v[76:77], v[126:127]
	ds_read_b128 v[88:91], v116 offset:5456
	s_waitcnt lgkmcnt(7)
	v_pk_fma_f32 v[124:125], v[92:93], v[72:73], v[124:125]
	v_pk_fma_f32 v[126:127], v[94:95], v[66:67], v[126:127]
	ds_read_b128 v[92:95], v116 offset:5632
	s_waitcnt lgkmcnt(7)
	v_pk_fma_f32 v[124:125], v[96:97], v[64:65], v[124:125]
	v_pk_add_f32 v[128:129], v[128:129], v[130:131]
	v_add_f32_e32 v133, v128, v129
	v_sub_f32_e32 v63, v63, v133
	v_pk_fma_f32 v[126:127], v[98:99], v[62:63], v[126:127]
	ds_read_b128 v[96:99], v116 offset:5648
	s_waitcnt lgkmcnt(7)
	v_pk_mul_f32 v[128:129], v[100:101], v[4:5] op_sel:[0,1] op_sel_hi:[1,0]
	v_pk_mul_f32 v[130:131], v[102:103], v[70:71]
	ds_read_b128 v[100:103], v116 offset:5664
	s_waitcnt lgkmcnt(7)
	v_pk_fma_f32 v[128:129], v[104:105], v[74:75], v[128:129]
	v_pk_fma_f32 v[130:131], v[106:107], v[80:81], v[130:131]
	ds_read_b128 v[104:107], v116 offset:5680
	s_waitcnt lgkmcnt(7)
	v_pk_fma_f32 v[128:129], v[108:109], v[78:79], v[128:129]
	v_pk_fma_f32 v[130:131], v[110:111], v[76:77], v[130:131]
	ds_read_b128 v[108:111], v116 offset:5696
	s_waitcnt lgkmcnt(7)
	v_pk_fma_f32 v[128:129], v[112:113], v[72:73], v[128:129]
	v_pk_fma_f32 v[130:131], v[114:115], v[66:67], v[130:131]
	ds_read_b128 v[112:115], v116 offset:5712
	s_waitcnt lgkmcnt(7)
	v_pk_fma_f32 v[128:129], v[84:85], v[64:65], v[128:129]
	v_pk_fma_f32 v[130:131], v[86:87], v[62:63], v[130:131]
	ds_read_b128 v[84:87], v116 offset:5888
	v_pk_add_f32 v[124:125], v[124:125], v[126:127]
	v_add_f32_e32 v132, v124, v125
	v_sub_f32_e32 v60, v60, v132
	s_waitcnt lgkmcnt(7)
	v_pk_fma_f32 v[128:129], v[88:89], v[60:61], v[128:129]
	ds_read_b128 v[88:91], v116 offset:5904
	s_waitcnt lgkmcnt(7)
	v_pk_mul_f32 v[124:125], v[92:93], v[4:5] op_sel:[0,1] op_sel_hi:[1,0]
	v_pk_mul_f32 v[126:127], v[94:95], v[70:71]
	ds_read_b128 v[92:95], v116 offset:5920
	s_waitcnt lgkmcnt(7)
	v_pk_fma_f32 v[124:125], v[96:97], v[74:75], v[124:125]
	v_pk_fma_f32 v[126:127], v[98:99], v[80:81], v[126:127]
	ds_read_b128 v[96:99], v116 offset:5936
	s_waitcnt lgkmcnt(7)
	v_pk_fma_f32 v[124:125], v[100:101], v[78:79], v[124:125]
	v_pk_fma_f32 v[126:127], v[102:103], v[76:77], v[126:127]
	ds_read_b128 v[100:103], v116 offset:5952
	s_waitcnt lgkmcnt(7)
	v_pk_fma_f32 v[124:125], v[104:105], v[72:73], v[124:125]
	v_pk_fma_f32 v[126:127], v[106:107], v[66:67], v[126:127]
	ds_read_b128 v[104:107], v116 offset:5968
	s_waitcnt lgkmcnt(7)
	v_pk_fma_f32 v[124:125], v[108:109], v[64:65], v[124:125]
	v_pk_fma_f32 v[126:127], v[110:111], v[62:63], v[126:127]
	ds_read_b128 v[108:111], v116 offset:6144
	v_pk_add_f32 v[128:129], v[128:129], v[130:131]
	v_add_f32_e32 v133, v128, v129
	v_sub_f32_e32 v61, v61, v133
	s_waitcnt lgkmcnt(7)
	v_pk_fma_f32 v[124:125], v[112:113], v[60:61], v[124:125]
	ds_read_b128 v[112:115], v116 offset:6160
	s_waitcnt lgkmcnt(7)
	v_pk_mul_f32 v[128:129], v[84:85], v[4:5] op_sel:[0,1] op_sel_hi:[1,0]
	v_pk_mul_f32 v[130:131], v[86:87], v[70:71]
	ds_read_b128 v[84:87], v116 offset:6176
	s_waitcnt lgkmcnt(7)
	v_pk_fma_f32 v[128:129], v[88:89], v[74:75], v[128:129]
	v_pk_fma_f32 v[130:131], v[90:91], v[80:81], v[130:131]
	ds_read_b128 v[88:91], v116 offset:6192
	s_waitcnt lgkmcnt(7)
	v_pk_fma_f32 v[128:129], v[92:93], v[78:79], v[128:129]
	v_pk_fma_f32 v[130:131], v[94:95], v[76:77], v[130:131]
	ds_read_b128 v[92:95], v116 offset:6208
	s_waitcnt lgkmcnt(7)
	v_pk_fma_f32 v[128:129], v[96:97], v[72:73], v[128:129]
	v_pk_fma_f32 v[130:131], v[98:99], v[66:67], v[130:131]
	ds_read_b128 v[96:99], v116 offset:6224
	s_waitcnt lgkmcnt(7)
	v_pk_fma_f32 v[128:129], v[100:101], v[64:65], v[128:129]
	v_pk_fma_f32 v[130:131], v[102:103], v[62:63], v[130:131]
	ds_read_b128 v[100:103], v116 offset:6400
	s_waitcnt lgkmcnt(7)
	v_pk_fma_f32 v[128:129], v[104:105], v[60:61], v[128:129]
	v_pk_add_f32 v[124:125], v[124:125], v[126:127]
	v_add_f32_e32 v132, v124, v125
	v_sub_f32_e32 v56, v56, v132
	v_pk_fma_f32 v[130:131], v[106:107], v[56:57], v[130:131]
	ds_read_b128 v[104:107], v116 offset:6416
	s_waitcnt lgkmcnt(7)
	v_pk_mul_f32 v[124:125], v[108:109], v[4:5] op_sel:[0,1] op_sel_hi:[1,0]
	v_pk_mul_f32 v[126:127], v[110:111], v[70:71]
	ds_read_b128 v[108:111], v116 offset:6432
	s_waitcnt lgkmcnt(7)
	v_pk_fma_f32 v[124:125], v[112:113], v[74:75], v[124:125]
	v_pk_fma_f32 v[126:127], v[114:115], v[80:81], v[126:127]
	ds_read_b128 v[112:115], v116 offset:6448
	s_waitcnt lgkmcnt(7)
	v_pk_fma_f32 v[124:125], v[84:85], v[78:79], v[124:125]
	v_pk_fma_f32 v[126:127], v[86:87], v[76:77], v[126:127]
	ds_read_b128 v[84:87], v116 offset:6464
	s_waitcnt lgkmcnt(7)
	v_pk_fma_f32 v[124:125], v[88:89], v[72:73], v[124:125]
	v_pk_fma_f32 v[126:127], v[90:91], v[66:67], v[126:127]
	ds_read_b128 v[88:91], v116 offset:6480
	s_waitcnt lgkmcnt(7)
; __device__ __forceinline__ void gd_prep_item(CArgs* a, LAS unsigned char* lds, int l, int item) {
;     ...
;         for (int t = 1; t < 64; ++t) nrow[t] = NM[t * 64 + lane];
; #pragma unroll
;         for (int t = 1; t < 64; ++t) { float s0 = 0.f, s1 = 0.f;
; #pragma unroll
;             for (int sI = 0; sI < t; ++sI) { const float cf = __builtin_bit_cast(float, __builtin_amdgcn_readlane(__builtin_bit_cast(int, nrow[t]), sI)); if (sI & 1) s1 += cf * x[sI]; else s0 += cf * x[sI]; }
;             x[t] -= s0 + s1; }
	v_pk_fma_f32 v[124:125], v[92:93], v[64:65], v[124:125]
	v_pk_fma_f32 v[126:127], v[94:95], v[62:63], v[126:127]
	ds_read_b128 v[92:95], v116 offset:6496
	s_waitcnt lgkmcnt(7)
	v_pk_fma_f32 v[124:125], v[96:97], v[60:61], v[124:125]
	v_pk_add_f32 v[128:129], v[128:129], v[130:131]
	v_add_f32_e32 v133, v128, v129
	v_sub_f32_e32 v57, v57, v133
	v_pk_fma_f32 v[126:127], v[98:99], v[56:57], v[126:127]
	ds_read_b128 v[96:99], v116 offset:6656
	s_waitcnt lgkmcnt(7)
	v_pk_mul_f32 v[128:129], v[100:101], v[4:5] op_sel:[0,1] op_sel_hi:[1,0]
	v_pk_mul_f32 v[130:131], v[102:103], v[70:71]
	ds_read_b128 v[100:103], v116 offset:6672
	s_waitcnt lgkmcnt(7)
	v_pk_fma_f32 v[128:129], v[104:105], v[74:75], v[128:129]
	v_pk_fma_f32 v[130:131], v[106:107], v[80:81], v[130:131]
	ds_read_b128 v[104:107], v116 offset:6688
	s_waitcnt lgkmcnt(7)
	v_pk_fma_f32 v[128:129], v[108:109], v[78:79], v[128:129]
	v_pk_fma_f32 v[130:131], v[110:111], v[76:77], v[130:131]
	ds_read_b128 v[108:111], v116 offset:6704
	s_waitcnt lgkmcnt(7)
	v_pk_fma_f32 v[128:129], v[112:113], v[72:73], v[128:129]
	v_pk_fma_f32 v[130:131], v[114:115], v[66:67], v[130:131]
	ds_read_b128 v[112:115], v116 offset:6720
	s_waitcnt lgkmcnt(7)
	v_pk_fma_f32 v[128:129], v[84:85], v[64:65], v[128:129]
	v_pk_fma_f32 v[130:131], v[86:87], v[62:63], v[130:131]
	ds_read_b128 v[84:87], v116 offset:6736
	s_waitcnt lgkmcnt(7)
	v_pk_fma_f32 v[128:129], v[88:89], v[60:61], v[128:129]
	v_pk_fma_f32 v[130:131], v[90:91], v[56:57], v[130:131]
	ds_read_b128 v[88:91], v116 offset:6752
	v_pk_add_f32 v[124:125], v[124:125], v[126:127]
	v_add_f32_e32 v132, v124, v125
	v_sub_f32_e32 v54, v54, v132
	s_waitcnt lgkmcnt(7)
	v_pk_fma_f32 v[128:129], v[92:93], v[54:55], v[128:129]
	ds_read_b128 v[92:95], v116 offset:6912
	s_waitcnt lgkmcnt(7)
	v_pk_mul_f32 v[124:125], v[96:97], v[4:5] op_sel:[0,1] op_sel_hi:[1,0]
	v_pk_mul_f32 v[126:127], v[98:99], v[70:71]
	ds_read_b128 v[96:99], v116 offset:6928
	s_waitcnt lgkmcnt(7)
	v_pk_fma_f32 v[124:125], v[100:101], v[74:75], v[124:125]
	v_pk_fma_f32 v[126:127], v[102:103], v[80:81], v[126:127]
	ds_read_b128 v[100:103], v116 offset:6944
	s_waitcnt lgkmcnt(7)
	v_pk_fma_f32 v[124:125], v[104:105], v[78:79], v[124:125]
	v_pk_fma_f32 v[126:127], v[106:107], v[76:77], v[126:127]
	ds_read_b128 v[104:107], v116 offset:6960
	s_waitcnt lgkmcnt(7)
	v_pk_fma_f32 v[124:125], v[108:109], v[72:73], v[124:125]
	v_pk_fma_f32 v[126:127], v[110:111], v[66:67], v[126:127]
	ds_read_b128 v[108:111], v116 offset:6976
	s_waitcnt lgkmcnt(7)
	v_pk_fma_f32 v[124:125], v[112:113], v[64:65], v[124:125]
	v_pk_fma_f32 v[126:127], v[114:115], v[62:63], v[126:127]
	ds_read_b128 v[112:115], v116 offset:6992
	s_waitcnt lgkmcnt(7)
	v_pk_fma_f32 v[124:125], v[84:85], v[60:61], v[124:125]
	v_pk_fma_f32 v[126:127], v[86:87], v[56:57], v[126:127]
	ds_read_b128 v[84:87], v116 offset:7008
	v_pk_add_f32 v[128:129], v[128:129], v[130:131]
	v_add_f32_e32 v133, v128, v129
	v_sub_f32_e32 v55, v55, v133
	s_waitcnt lgkmcnt(7)
	v_pk_fma_f32 v[124:125], v[88:89], v[54:55], v[124:125]
	ds_read_b128 v[88:91], v116 offset:7168
	s_waitcnt lgkmcnt(7)
	v_pk_mul_f32 v[128:129], v[92:93], v[4:5] op_sel:[0,1] op_sel_hi:[1,0]
	v_pk_mul_f32 v[130:131], v[94:95], v[70:71]
	ds_read_b128 v[92:95], v116 offset:7184
	s_waitcnt lgkmcnt(7)
	v_pk_fma_f32 v[128:129], v[96:97], v[74:75], v[128:129]
	v_pk_fma_f32 v[130:131], v[98:99], v[80:81], v[130:131]
	ds_read_b128 v[96:99], v116 offset:7200
	s_waitcnt lgkmcnt(7)
	v_pk_fma_f32 v[128:129], v[100:101], v[78:79], v[128:129]
	v_pk_fma_f32 v[130:131], v[102:103], v[76:77], v[130:131]
	ds_read_b128 v[100:103], v116 offset:7216
	s_waitcnt lgkmcnt(7)
	v_pk_fma_f32 v[128:129], v[104:105], v[72:73], v[128:129]
	v_pk_fma_f32 v[130:131], v[106:107], v[66:67], v[130:131]
	ds_read_b128 v[104:107], v116 offset:7232
	s_waitcnt lgkmcnt(7)
	v_pk_fma_f32 v[128:129], v[108:109], v[64:65], v[128:129]
	v_pk_fma_f32 v[130:131], v[110:111], v[62:63], v[130:131]
	ds_read_b128 v[108:111], v116 offset:7248
	s_waitcnt lgkmcnt(7)
	v_pk_fma_f32 v[128:129], v[112:113], v[60:61], v[128:129]
	v_pk_fma_f32 v[130:131], v[114:115], v[56:57], v[130:131]
	ds_read_b128 v[112:115], v116 offset:7264
	s_waitcnt lgkmcnt(7)
	v_pk_fma_f32 v[128:129], v[84:85], v[54:55], v[128:129]
	v_pk_add_f32 v[124:125], v[124:125], v[126:127]
	v_add_f32_e32 v132, v124, v125
	v_sub_f32_e32 v52, v52, v132
	v_pk_fma_f32 v[130:131], v[86:87], v[52:53], v[130:131]
	ds_read_b128 v[84:87], v116 offset:7424
	s_waitcnt lgkmcnt(7)
	v_pk_mul_f32 v[124:125], v[88:89], v[4:5] op_sel:[0,1] op_sel_hi:[1,0]
	v_pk_mul_f32 v[126:127], v[90:91], v[70:71]
	ds_read_b128 v[88:91], v116 offset:7440
	s_waitcnt lgkmcnt(7)
	v_pk_fma_f32 v[124:125], v[92:93], v[74:75], v[124:125]
	v_pk_fma_f32 v[126:127], v[94:95], v[80:81], v[126:127]
	ds_read_b128 v[92:95], v116 offset:7456
	s_waitcnt lgkmcnt(7)
	v_pk_fma_f32 v[124:125], v[96:97], v[78:79], v[124:125]
	v_pk_fma_f32 v[126:127], v[98:99], v[76:77], v[126:127]
	ds_read_b128 v[96:99], v116 offset:7472
	s_waitcnt lgkmcnt(7)
	v_pk_fma_f32 v[124:125], v[100:101], v[72:73], v[124:125]
	v_pk_fma_f32 v[126:127], v[102:103], v[66:67], v[126:127]
	ds_read_b128 v[100:103], v116 offset:7488
	s_waitcnt lgkmcnt(7)
	v_pk_fma_f32 v[124:125], v[104:105], v[64:65], v[124:125]
	v_pk_fma_f32 v[126:127], v[106:107], v[62:63], v[126:127]
	ds_read_b128 v[104:107], v116 offset:7504
	s_waitcnt lgkmcnt(7)
	v_pk_fma_f32 v[124:125], v[108:109], v[60:61], v[124:125]
	v_pk_fma_f32 v[126:127], v[110:111], v[56:57], v[126:127]
	ds_read_b128 v[108:111], v116 offset:7520
	s_waitcnt lgkmcnt(7)
; __device__ __forceinline__ void gd_prep_item(CArgs* a, LAS unsigned char* lds, int l, int item) {
;     ...
;         for (int t = 1; t < 64; ++t) nrow[t] = NM[t * 64 + lane];
; #pragma unroll
;         for (int t = 1; t < 64; ++t) { float s0 = 0.f, s1 = 0.f;
; #pragma unroll
;             for (int sI = 0; sI < t; ++sI) { const float cf = __builtin_bit_cast(float, __builtin_amdgcn_readlane(__builtin_bit_cast(int, nrow[t]), sI)); if (sI & 1) s1 += cf * x[sI]; else s0 += cf * x[sI]; }
;             x[t] -= s0 + s1; }
	v_pk_fma_f32 v[124:125], v[112:113], v[54:55], v[124:125]
	v_pk_add_f32 v[128:129], v[128:129], v[130:131]
	v_add_f32_e32 v133, v128, v129
	v_sub_f32_e32 v53, v53, v133
	v_pk_fma_f32 v[126:127], v[114:115], v[52:53], v[126:127]
	ds_read_b128 v[112:115], v116 offset:7536
	s_waitcnt lgkmcnt(7)
	v_pk_mul_f32 v[128:129], v[84:85], v[4:5] op_sel:[0,1] op_sel_hi:[1,0]
	v_pk_mul_f32 v[130:131], v[86:87], v[70:71]
	ds_read_b128 v[84:87], v116 offset:7680
	s_waitcnt lgkmcnt(7)
	v_pk_fma_f32 v[128:129], v[88:89], v[74:75], v[128:129]
	v_pk_fma_f32 v[130:131], v[90:91], v[80:81], v[130:131]
	ds_read_b128 v[88:91], v116 offset:7696
	s_waitcnt lgkmcnt(7)
	v_pk_fma_f32 v[128:129], v[92:93], v[78:79], v[128:129]
	v_pk_fma_f32 v[130:131], v[94:95], v[76:77], v[130:131]
	ds_read_b128 v[92:95], v116 offset:7712
	s_waitcnt lgkmcnt(7)
	v_pk_fma_f32 v[128:129], v[96:97], v[72:73], v[128:129]
	v_pk_fma_f32 v[130:131], v[98:99], v[66:67], v[130:131]
	ds_read_b128 v[96:99], v116 offset:7728
	s_waitcnt lgkmcnt(7)
	v_pk_fma_f32 v[128:129], v[100:101], v[64:65], v[128:129]
	v_pk_fma_f32 v[130:131], v[102:103], v[62:63], v[130:131]
	ds_read_b128 v[100:103], v116 offset:7744
	s_waitcnt lgkmcnt(7)
	v_pk_fma_f32 v[128:129], v[104:105], v[60:61], v[128:129]
	v_pk_fma_f32 v[130:131], v[106:107], v[56:57], v[130:131]
	ds_read_b128 v[104:107], v116 offset:7760
	s_waitcnt lgkmcnt(7)
	v_pk_fma_f32 v[128:129], v[108:109], v[54:55], v[128:129]
	v_pk_fma_f32 v[130:131], v[110:111], v[52:53], v[130:131]
	ds_read_b128 v[108:111], v116 offset:7776
	v_pk_add_f32 v[124:125], v[124:125], v[126:127]
	v_add_f32_e32 v132, v124, v125
	v_sub_f32_e32 v48, v48, v132
	s_waitcnt lgkmcnt(7)
	v_pk_fma_f32 v[128:129], v[112:113], v[48:49], v[128:129]
	ds_read_b128 v[112:115], v116 offset:7792
	s_waitcnt lgkmcnt(7)
	v_pk_mul_f32 v[124:125], v[84:85], v[4:5] op_sel:[0,1] op_sel_hi:[1,0]
	v_pk_mul_f32 v[126:127], v[86:87], v[70:71]
	ds_read_b128 v[84:87], v116 offset:7936
	s_waitcnt lgkmcnt(7)
	v_pk_fma_f32 v[124:125], v[88:89], v[74:75], v[124:125]
	v_pk_fma_f32 v[126:127], v[90:91], v[80:81], v[126:127]
	ds_read_b128 v[88:91], v116 offset:7952
	s_waitcnt lgkmcnt(7)
	v_pk_fma_f32 v[124:125], v[92:93], v[78:79], v[124:125]
	v_pk_fma_f32 v[126:127], v[94:95], v[76:77], v[126:127]
	ds_read_b128 v[92:95], v116 offset:7968
	s_waitcnt lgkmcnt(7)
	v_pk_fma_f32 v[124:125], v[96:97], v[72:73], v[124:125]
	v_pk_fma_f32 v[126:127], v[98:99], v[66:67], v[126:127]
	ds_read_b128 v[96:99], v116 offset:7984
	s_waitcnt lgkmcnt(7)
	v_pk_fma_f32 v[124:125], v[100:101], v[64:65], v[124:125]
	v_pk_fma_f32 v[126:127], v[102:103], v[62:63], v[126:127]
	ds_read_b128 v[100:103], v116 offset:8000
	s_waitcnt lgkmcnt(7)
	v_pk_fma_f32 v[124:125], v[104:105], v[60:61], v[124:125]
	v_pk_fma_f32 v[126:127], v[106:107], v[56:57], v[126:127]
	ds_read_b128 v[104:107], v116 offset:8016
	s_waitcnt lgkmcnt(7)
	v_pk_fma_f32 v[124:125], v[108:109], v[54:55], v[124:125]
	v_pk_fma_f32 v[126:127], v[110:111], v[52:53], v[126:127]
	ds_read_b128 v[108:111], v116 offset:8032
	v_pk_add_f32 v[128:129], v[128:129], v[130:131]
	v_add_f32_e32 v133, v128, v129
	v_sub_f32_e32 v49, v49, v133
	s_waitcnt lgkmcnt(7)
	v_pk_fma_f32 v[124:125], v[112:113], v[48:49], v[124:125]
	ds_read_b128 v[112:115], v116 offset:8048
	s_waitcnt lgkmcnt(7)
	v_pk_mul_f32 v[128:129], v[84:85], v[4:5] op_sel:[0,1] op_sel_hi:[1,0]
	v_pk_mul_f32 v[130:131], v[86:87], v[70:71]
	ds_read_b128 v[84:87], v116 offset:8192
	s_waitcnt lgkmcnt(7)
	v_pk_fma_f32 v[128:129], v[88:89], v[74:75], v[128:129]
	v_pk_fma_f32 v[130:131], v[90:91], v[80:81], v[130:131]
	ds_read_b128 v[88:91], v116 offset:8208
	s_waitcnt lgkmcnt(7)
	v_pk_fma_f32 v[128:129], v[92:93], v[78:79], v[128:129]
	v_pk_fma_f32 v[130:131], v[94:95], v[76:77], v[130:131]
	ds_read_b128 v[92:95], v116 offset:8224
	s_waitcnt lgkmcnt(7)
	v_pk_fma_f32 v[128:129], v[96:97], v[72:73], v[128:129]
	v_pk_fma_f32 v[130:131], v[98:99], v[66:67], v[130:131]
	ds_read_b128 v[96:99], v116 offset:8240
	s_waitcnt lgkmcnt(7)
	v_pk_fma_f32 v[128:129], v[100:101], v[64:65], v[128:129]
	v_pk_fma_f32 v[130:131], v[102:103], v[62:63], v[130:131]
	ds_read_b128 v[100:103], v116 offset:8256
	s_waitcnt lgkmcnt(7)
	v_pk_fma_f32 v[128:129], v[104:105], v[60:61], v[128:129]
	v_pk_fma_f32 v[130:131], v[106:107], v[56:57], v[130:131]
	ds_read_b128 v[104:107], v116 offset:8272
	s_waitcnt lgkmcnt(7)
	v_pk_fma_f32 v[128:129], v[108:109], v[54:55], v[128:129]
	v_pk_fma_f32 v[130:131], v[110:111], v[52:53], v[130:131]
	ds_read_b128 v[108:111], v116 offset:8288
	s_waitcnt lgkmcnt(7)
	v_pk_fma_f32 v[128:129], v[112:113], v[48:49], v[128:129]
	v_pk_add_f32 v[124:125], v[124:125], v[126:127]
	v_add_f32_e32 v132, v124, v125
	v_sub_f32_e32 v46, v46, v132
	v_pk_fma_f32 v[130:131], v[114:115], v[46:47], v[130:131]
	ds_read_b128 v[112:115], v116 offset:8304
	s_waitcnt lgkmcnt(7)
	v_pk_mul_f32 v[124:125], v[84:85], v[4:5] op_sel:[0,1] op_sel_hi:[1,0]
	v_pk_mul_f32 v[126:127], v[86:87], v[70:71]
	ds_read_b128 v[84:87], v116 offset:8448
	s_waitcnt lgkmcnt(7)
	v_pk_fma_f32 v[124:125], v[88:89], v[74:75], v[124:125]
	v_pk_fma_f32 v[126:127], v[90:91], v[80:81], v[126:127]
	ds_read_b128 v[88:91], v116 offset:8464
	s_waitcnt lgkmcnt(7)
	v_pk_fma_f32 v[124:125], v[92:93], v[78:79], v[124:125]
	v_pk_fma_f32 v[126:127], v[94:95], v[76:77], v[126:127]
	ds_read_b128 v[92:95], v116 offset:8480
	s_waitcnt lgkmcnt(7)
	v_pk_fma_f32 v[124:125], v[96:97], v[72:73], v[124:125]
	v_pk_fma_f32 v[126:127], v[98:99], v[66:67], v[126:127]
	ds_read_b128 v[96:99], v116 offset:8496
	s_waitcnt lgkmcnt(7)
; __device__ __forceinline__ void gd_prep_item(CArgs* a, LAS unsigned char* lds, int l, int item) {
;     ...
;         for (int t = 1; t < 64; ++t) nrow[t] = NM[t * 64 + lane];
; #pragma unroll
;         for (int t = 1; t < 64; ++t) { float s0 = 0.f, s1 = 0.f;
; #pragma unroll
;             for (int sI = 0; sI < t; ++sI) { const float cf = __builtin_bit_cast(float, __builtin_amdgcn_readlane(__builtin_bit_cast(int, nrow[t]), sI)); if (sI & 1) s1 += cf * x[sI]; else s0 += cf * x[sI]; }
;             x[t] -= s0 + s1; }
	v_pk_fma_f32 v[124:125], v[100:101], v[64:65], v[124:125]
	v_pk_fma_f32 v[126:127], v[102:103], v[62:63], v[126:127]
	ds_read_b128 v[100:103], v116 offset:8512
	s_waitcnt lgkmcnt(7)
	v_pk_fma_f32 v[124:125], v[104:105], v[60:61], v[124:125]
	v_pk_fma_f32 v[126:127], v[106:107], v[56:57], v[126:127]
	ds_read_b128 v[104:107], v116 offset:8528
	s_waitcnt lgkmcnt(7)
	v_pk_fma_f32 v[124:125], v[108:109], v[54:55], v[124:125]
	v_pk_fma_f32 v[126:127], v[110:111], v[52:53], v[126:127]
	ds_read_b128 v[108:111], v116 offset:8544
	s_waitcnt lgkmcnt(7)
	v_pk_fma_f32 v[124:125], v[112:113], v[48:49], v[124:125]
	v_pk_add_f32 v[128:129], v[128:129], v[130:131]
	v_add_f32_e32 v133, v128, v129
	v_sub_f32_e32 v47, v47, v133
	v_pk_fma_f32 v[126:127], v[114:115], v[46:47], v[126:127]
	ds_read_b128 v[112:115], v116 offset:8560
	s_waitcnt lgkmcnt(7)
	v_pk_mul_f32 v[128:129], v[84:85], v[4:5] op_sel:[0,1] op_sel_hi:[1,0]
	v_pk_mul_f32 v[130:131], v[86:87], v[70:71]
	ds_read_b128 v[84:87], v116 offset:8576
	s_waitcnt lgkmcnt(7)
	v_pk_fma_f32 v[128:129], v[88:89], v[74:75], v[128:129]
	v_pk_fma_f32 v[130:131], v[90:91], v[80:81], v[130:131]
	ds_read_b128 v[88:91], v116 offset:8704
	s_waitcnt lgkmcnt(7)
	v_pk_fma_f32 v[128:129], v[92:93], v[78:79], v[128:129]
	v_pk_fma_f32 v[130:131], v[94:95], v[76:77], v[130:131]
	ds_read_b128 v[92:95], v116 offset:8720
	s_waitcnt lgkmcnt(7)
	v_pk_fma_f32 v[128:129], v[96:97], v[72:73], v[128:129]
	v_pk_fma_f32 v[130:131], v[98:99], v[66:67], v[130:131]
	ds_read_b128 v[96:99], v116 offset:8736
	s_waitcnt lgkmcnt(7)
	v_pk_fma_f32 v[128:129], v[100:101], v[64:65], v[128:129]
	v_pk_fma_f32 v[130:131], v[102:103], v[62:63], v[130:131]
	ds_read_b128 v[100:103], v116 offset:8752
	s_waitcnt lgkmcnt(7)
	v_pk_fma_f32 v[128:129], v[104:105], v[60:61], v[128:129]
	v_pk_fma_f32 v[130:131], v[106:107], v[56:57], v[130:131]
	ds_read_b128 v[104:107], v116 offset:8768
	s_waitcnt lgkmcnt(7)
	v_pk_fma_f32 v[128:129], v[108:109], v[54:55], v[128:129]
	v_pk_fma_f32 v[130:131], v[110:111], v[52:53], v[130:131]
	ds_read_b128 v[108:111], v116 offset:8784
	s_waitcnt lgkmcnt(7)
	v_pk_fma_f32 v[128:129], v[112:113], v[48:49], v[128:129]
	v_pk_fma_f32 v[130:131], v[114:115], v[46:47], v[130:131]
	ds_read_b128 v[112:115], v116 offset:8800
	v_pk_add_f32 v[124:125], v[124:125], v[126:127]
	v_add_f32_e32 v132, v124, v125
	v_sub_f32_e32 v42, v42, v132
	s_waitcnt lgkmcnt(7)
	v_pk_fma_f32 v[128:129], v[84:85], v[42:43], v[128:129]
	ds_read_b128 v[84:87], v116 offset:8816
	s_waitcnt lgkmcnt(7)
	v_pk_mul_f32 v[124:125], v[88:89], v[4:5] op_sel:[0,1] op_sel_hi:[1,0]
	v_pk_mul_f32 v[126:127], v[90:91], v[70:71]
	ds_read_b128 v[88:91], v116 offset:8832
	s_waitcnt lgkmcnt(7)
	v_pk_fma_f32 v[124:125], v[92:93], v[74:75], v[124:125]
	v_pk_fma_f32 v[126:127], v[94:95], v[80:81], v[126:127]
	ds_read_b128 v[92:95], v116 offset:8960
	s_waitcnt lgkmcnt(7)
	v_pk_fma_f32 v[124:125], v[96:97], v[78:79], v[124:125]
	v_pk_fma_f32 v[126:127], v[98:99], v[76:77], v[126:127]
	ds_read_b128 v[96:99], v116 offset:8976
	s_waitcnt lgkmcnt(7)
	v_pk_fma_f32 v[124:125], v[100:101], v[72:73], v[124:125]
	v_pk_fma_f32 v[126:127], v[102:103], v[66:67], v[126:127]
	ds_read_b128 v[100:103], v116 offset:8992
	s_waitcnt lgkmcnt(7)
	v_pk_fma_f32 v[124:125], v[104:105], v[64:65], v[124:125]
	v_pk_fma_f32 v[126:127], v[106:107], v[62:63], v[126:127]
	ds_read_b128 v[104:107], v116 offset:9008
	s_waitcnt lgkmcnt(7)
	v_pk_fma_f32 v[124:125], v[108:109], v[60:61], v[124:125]
	v_pk_fma_f32 v[126:127], v[110:111], v[56:57], v[126:127]
	ds_read_b128 v[108:111], v116 offset:9024
	s_waitcnt lgkmcnt(7)
	v_pk_fma_f32 v[124:125], v[112:113], v[54:55], v[124:125]
	v_pk_fma_f32 v[126:127], v[114:115], v[52:53], v[126:127]
	ds_read_b128 v[112:115], v116 offset:9040
	s_waitcnt lgkmcnt(7)
	v_pk_fma_f32 v[124:125], v[84:85], v[48:49], v[124:125]
	v_pk_fma_f32 v[126:127], v[86:87], v[46:47], v[126:127]
	ds_read_b128 v[84:87], v116 offset:9056
	v_pk_add_f32 v[128:129], v[128:129], v[130:131]
	v_add_f32_e32 v133, v128, v129
	v_sub_f32_e32 v43, v43, v133
	s_waitcnt lgkmcnt(7)
	v_pk_fma_f32 v[124:125], v[88:89], v[42:43], v[124:125]
	ds_read_b128 v[88:91], v116 offset:9072
	s_waitcnt lgkmcnt(7)
	v_pk_mul_f32 v[128:129], v[92:93], v[4:5] op_sel:[0,1] op_sel_hi:[1,0]
	v_pk_mul_f32 v[130:131], v[94:95], v[70:71]
	ds_read_b128 v[92:95], v116 offset:9088
	s_waitcnt lgkmcnt(7)
	v_pk_fma_f32 v[128:129], v[96:97], v[74:75], v[128:129]
	v_pk_fma_f32 v[130:131], v[98:99], v[80:81], v[130:131]
	ds_read_b128 v[96:99], v116 offset:9216
	s_waitcnt lgkmcnt(7)
	v_pk_fma_f32 v[128:129], v[100:101], v[78:79], v[128:129]
	v_pk_fma_f32 v[130:131], v[102:103], v[76:77], v[130:131]
	ds_read_b128 v[100:103], v116 offset:9232
	s_waitcnt lgkmcnt(7)
	v_pk_fma_f32 v[128:129], v[104:105], v[72:73], v[128:129]
	v_pk_fma_f32 v[130:131], v[106:107], v[66:67], v[130:131]
	ds_read_b128 v[104:107], v116 offset:9248
	s_waitcnt lgkmcnt(7)
	v_pk_fma_f32 v[128:129], v[108:109], v[64:65], v[128:129]
	v_pk_fma_f32 v[130:131], v[110:111], v[62:63], v[130:131]
	ds_read_b128 v[108:111], v116 offset:9264
	s_waitcnt lgkmcnt(7)
	v_pk_fma_f32 v[128:129], v[112:113], v[60:61], v[128:129]
	v_pk_fma_f32 v[130:131], v[114:115], v[56:57], v[130:131]
	ds_read_b128 v[112:115], v116 offset:9280
	s_waitcnt lgkmcnt(7)
	v_pk_fma_f32 v[128:129], v[84:85], v[54:55], v[128:129]
	v_pk_fma_f32 v[130:131], v[86:87], v[52:53], v[130:131]
	ds_read_b128 v[84:87], v116 offset:9296
	s_waitcnt lgkmcnt(7)
	v_pk_fma_f32 v[128:129], v[88:89], v[48:49], v[128:129]
	v_pk_fma_f32 v[130:131], v[90:91], v[46:47], v[130:131]
	ds_read_b128 v[88:91], v116 offset:9312
	s_waitcnt lgkmcnt(7)
; __device__ __forceinline__ void gd_prep_item(CArgs* a, LAS unsigned char* lds, int l, int item) {
;     ...
;         for (int t = 1; t < 64; ++t) nrow[t] = NM[t * 64 + lane];
; #pragma unroll
;         for (int t = 1; t < 64; ++t) { float s0 = 0.f, s1 = 0.f;
; #pragma unroll
;             for (int sI = 0; sI < t; ++sI) { const float cf = __builtin_bit_cast(float, __builtin_amdgcn_readlane(__builtin_bit_cast(int, nrow[t]), sI)); if (sI & 1) s1 += cf * x[sI]; else s0 += cf * x[sI]; }
;             x[t] -= s0 + s1; }
	v_pk_fma_f32 v[128:129], v[92:93], v[42:43], v[128:129]
	v_pk_add_f32 v[124:125], v[124:125], v[126:127]
	v_add_f32_e32 v132, v124, v125
	v_sub_f32_e32 v40, v40, v132
	v_pk_fma_f32 v[130:131], v[94:95], v[40:41], v[130:131]
	ds_read_b128 v[92:95], v116 offset:9328
	s_waitcnt lgkmcnt(7)
	v_pk_mul_f32 v[124:125], v[96:97], v[4:5] op_sel:[0,1] op_sel_hi:[1,0]
	v_pk_mul_f32 v[126:127], v[98:99], v[70:71]
	ds_read_b128 v[96:99], v116 offset:9344
	s_waitcnt lgkmcnt(7)
	v_pk_fma_f32 v[124:125], v[100:101], v[74:75], v[124:125]
	v_pk_fma_f32 v[126:127], v[102:103], v[80:81], v[126:127]
	ds_read_b128 v[100:103], v116 offset:9472
	s_waitcnt lgkmcnt(7)
	v_pk_fma_f32 v[124:125], v[104:105], v[78:79], v[124:125]
	v_pk_fma_f32 v[126:127], v[106:107], v[76:77], v[126:127]
	ds_read_b128 v[104:107], v116 offset:9488
	s_waitcnt lgkmcnt(7)
	v_pk_fma_f32 v[124:125], v[108:109], v[72:73], v[124:125]
	v_pk_fma_f32 v[126:127], v[110:111], v[66:67], v[126:127]
	ds_read_b128 v[108:111], v116 offset:9504
	s_waitcnt lgkmcnt(7)
	v_pk_fma_f32 v[124:125], v[112:113], v[64:65], v[124:125]
	v_pk_fma_f32 v[126:127], v[114:115], v[62:63], v[126:127]
	ds_read_b128 v[112:115], v116 offset:9520
	s_waitcnt lgkmcnt(7)
	v_pk_fma_f32 v[124:125], v[84:85], v[60:61], v[124:125]
	v_pk_fma_f32 v[126:127], v[86:87], v[56:57], v[126:127]
	ds_read_b128 v[84:87], v116 offset:9536
	s_waitcnt lgkmcnt(7)
	v_pk_fma_f32 v[124:125], v[88:89], v[54:55], v[124:125]
	v_pk_fma_f32 v[126:127], v[90:91], v[52:53], v[126:127]
	ds_read_b128 v[88:91], v116 offset:9552
	s_waitcnt lgkmcnt(7)
	v_pk_fma_f32 v[124:125], v[92:93], v[48:49], v[124:125]
	v_pk_fma_f32 v[126:127], v[94:95], v[46:47], v[126:127]
	ds_read_b128 v[92:95], v116 offset:9568
	s_waitcnt lgkmcnt(7)
	v_pk_fma_f32 v[124:125], v[96:97], v[42:43], v[124:125]
	v_pk_add_f32 v[128:129], v[128:129], v[130:131]
	v_add_f32_e32 v133, v128, v129
	v_sub_f32_e32 v41, v41, v133
	v_pk_fma_f32 v[126:127], v[98:99], v[40:41], v[126:127]
	ds_read_b128 v[96:99], v116 offset:9584
	s_waitcnt lgkmcnt(7)
	v_pk_mul_f32 v[128:129], v[100:101], v[4:5] op_sel:[0,1] op_sel_hi:[1,0]
	v_pk_mul_f32 v[130:131], v[102:103], v[70:71]
	ds_read_b128 v[100:103], v116 offset:9600
	s_waitcnt lgkmcnt(7)
	v_pk_fma_f32 v[128:129], v[104:105], v[74:75], v[128:129]
	v_pk_fma_f32 v[130:131], v[106:107], v[80:81], v[130:131]
	ds_read_b128 v[104:107], v116 offset:9616
	s_waitcnt lgkmcnt(7)
	v_pk_fma_f32 v[128:129], v[108:109], v[78:79], v[128:129]
	v_pk_fma_f32 v[130:131], v[110:111], v[76:77], v[130:131]
	ds_read_b128 v[108:111], v116 offset:9728
	s_waitcnt lgkmcnt(7)
	v_pk_fma_f32 v[128:129], v[112:113], v[72:73], v[128:129]
	v_pk_fma_f32 v[130:131], v[114:115], v[66:67], v[130:131]
	ds_read_b128 v[112:115], v116 offset:9744
	s_waitcnt lgkmcnt(7)
	v_pk_fma_f32 v[128:129], v[84:85], v[64:65], v[128:129]
	v_pk_fma_f32 v[130:131], v[86:87], v[62:63], v[130:131]
	ds_read_b128 v[84:87], v116 offset:9760
	s_waitcnt lgkmcnt(7)
	v_pk_fma_f32 v[128:129], v[88:89], v[60:61], v[128:129]
	v_pk_fma_f32 v[130:131], v[90:91], v[56:57], v[130:131]
	ds_read_b128 v[88:91], v116 offset:9776
	s_waitcnt lgkmcnt(7)
	v_pk_fma_f32 v[128:129], v[92:93], v[54:55], v[128:129]
	v_pk_fma_f32 v[130:131], v[94:95], v[52:53], v[130:131]
	ds_read_b128 v[92:95], v116 offset:9792
	s_waitcnt lgkmcnt(7)
	v_pk_fma_f32 v[128:129], v[96:97], v[48:49], v[128:129]
	v_pk_fma_f32 v[130:131], v[98:99], v[46:47], v[130:131]
	ds_read_b128 v[96:99], v116 offset:9808
	s_waitcnt lgkmcnt(7)
	v_pk_fma_f32 v[128:129], v[100:101], v[42:43], v[128:129]
	v_pk_fma_f32 v[130:131], v[102:103], v[40:41], v[130:131]
	ds_read_b128 v[100:103], v116 offset:9824
	v_pk_add_f32 v[124:125], v[124:125], v[126:127]
	v_add_f32_e32 v132, v124, v125
	v_sub_f32_e32 v36, v36, v132
	s_waitcnt lgkmcnt(7)
	v_pk_fma_f32 v[128:129], v[104:105], v[36:37], v[128:129]
	ds_read_b128 v[104:107], v116 offset:9840
	s_waitcnt lgkmcnt(7)
	v_pk_mul_f32 v[124:125], v[108:109], v[4:5] op_sel:[0,1] op_sel_hi:[1,0]
	v_pk_mul_f32 v[126:127], v[110:111], v[70:71]
	ds_read_b128 v[108:111], v116 offset:9856
	s_waitcnt lgkmcnt(7)
	v_pk_fma_f32 v[124:125], v[112:113], v[74:75], v[124:125]
	v_pk_fma_f32 v[126:127], v[114:115], v[80:81], v[126:127]
	ds_read_b128 v[112:115], v116 offset:9872
	s_waitcnt lgkmcnt(7)
	v_pk_fma_f32 v[124:125], v[84:85], v[78:79], v[124:125]
	v_pk_fma_f32 v[126:127], v[86:87], v[76:77], v[126:127]
	ds_read_b128 v[84:87], v116 offset:9984
	s_waitcnt lgkmcnt(7)
	v_pk_fma_f32 v[124:125], v[88:89], v[72:73], v[124:125]
	v_pk_fma_f32 v[126:127], v[90:91], v[66:67], v[126:127]
	ds_read_b128 v[88:91], v116 offset:10000
	s_waitcnt lgkmcnt(7)
	v_pk_fma_f32 v[124:125], v[92:93], v[64:65], v[124:125]
	v_pk_fma_f32 v[126:127], v[94:95], v[62:63], v[126:127]
	ds_read_b128 v[92:95], v116 offset:10016
	s_waitcnt lgkmcnt(7)
	v_pk_fma_f32 v[124:125], v[96:97], v[60:61], v[124:125]
	v_pk_fma_f32 v[126:127], v[98:99], v[56:57], v[126:127]
	ds_read_b128 v[96:99], v116 offset:10032
	s_waitcnt lgkmcnt(7)
	v_pk_fma_f32 v[124:125], v[100:101], v[54:55], v[124:125]
	v_pk_fma_f32 v[126:127], v[102:103], v[52:53], v[126:127]
	ds_read_b128 v[100:103], v116 offset:10048
	s_waitcnt lgkmcnt(7)
	v_pk_fma_f32 v[124:125], v[104:105], v[48:49], v[124:125]
	v_pk_fma_f32 v[126:127], v[106:107], v[46:47], v[126:127]
	ds_read_b128 v[104:107], v116 offset:10064
	s_waitcnt lgkmcnt(7)
	v_pk_fma_f32 v[124:125], v[108:109], v[42:43], v[124:125]
	v_pk_fma_f32 v[126:127], v[110:111], v[40:41], v[126:127]
	ds_read_b128 v[108:111], v116 offset:10080
	v_pk_add_f32 v[128:129], v[128:129], v[130:131]
	v_add_f32_e32 v133, v128, v129
	v_sub_f32_e32 v37, v37, v133
	s_waitcnt lgkmcnt(7)
; __device__ __forceinline__ void gd_prep_item(CArgs* a, LAS unsigned char* lds, int l, int item) {
;     ...
;         for (int t = 1; t < 64; ++t) nrow[t] = NM[t * 64 + lane];
; #pragma unroll
;         for (int t = 1; t < 64; ++t) { float s0 = 0.f, s1 = 0.f;
; #pragma unroll
;             for (int sI = 0; sI < t; ++sI) { const float cf = __builtin_bit_cast(float, __builtin_amdgcn_readlane(__builtin_bit_cast(int, nrow[t]), sI)); if (sI & 1) s1 += cf * x[sI]; else s0 += cf * x[sI]; }
;             x[t] -= s0 + s1; }
	v_pk_fma_f32 v[124:125], v[112:113], v[36:37], v[124:125]
	ds_read_b128 v[112:115], v116 offset:10096
	s_waitcnt lgkmcnt(7)
	v_pk_mul_f32 v[128:129], v[84:85], v[4:5] op_sel:[0,1] op_sel_hi:[1,0]
	v_pk_mul_f32 v[130:131], v[86:87], v[70:71]
	ds_read_b128 v[84:87], v116 offset:10112
	s_waitcnt lgkmcnt(7)
	v_pk_fma_f32 v[128:129], v[88:89], v[74:75], v[128:129]
	v_pk_fma_f32 v[130:131], v[90:91], v[80:81], v[130:131]
	ds_read_b128 v[88:91], v116 offset:10128
	s_waitcnt lgkmcnt(7)
	v_pk_fma_f32 v[128:129], v[92:93], v[78:79], v[128:129]
	v_pk_fma_f32 v[130:131], v[94:95], v[76:77], v[130:131]
	ds_read_b128 v[92:95], v116 offset:10240
	s_waitcnt lgkmcnt(7)
	v_pk_fma_f32 v[128:129], v[96:97], v[72:73], v[128:129]
	v_pk_fma_f32 v[130:131], v[98:99], v[66:67], v[130:131]
	ds_read_b128 v[96:99], v116 offset:10256
	s_waitcnt lgkmcnt(7)
	v_pk_fma_f32 v[128:129], v[100:101], v[64:65], v[128:129]
	v_pk_fma_f32 v[130:131], v[102:103], v[62:63], v[130:131]
	ds_read_b128 v[100:103], v116 offset:10272
	s_waitcnt lgkmcnt(7)
	v_pk_fma_f32 v[128:129], v[104:105], v[60:61], v[128:129]
	v_pk_fma_f32 v[130:131], v[106:107], v[56:57], v[130:131]
	ds_read_b128 v[104:107], v116 offset:10288
	s_waitcnt lgkmcnt(7)
	v_pk_fma_f32 v[128:129], v[108:109], v[54:55], v[128:129]
	v_pk_fma_f32 v[130:131], v[110:111], v[52:53], v[130:131]
	ds_read_b128 v[108:111], v116 offset:10304
	s_waitcnt lgkmcnt(7)
	v_pk_fma_f32 v[128:129], v[112:113], v[48:49], v[128:129]
	v_pk_fma_f32 v[130:131], v[114:115], v[46:47], v[130:131]
	ds_read_b128 v[112:115], v116 offset:10320
	s_waitcnt lgkmcnt(7)
	v_pk_fma_f32 v[128:129], v[84:85], v[42:43], v[128:129]
	v_pk_fma_f32 v[130:131], v[86:87], v[40:41], v[130:131]
	ds_read_b128 v[84:87], v116 offset:10336
	s_waitcnt lgkmcnt(7)
	v_pk_fma_f32 v[128:129], v[88:89], v[36:37], v[128:129]
	v_pk_add_f32 v[124:125], v[124:125], v[126:127]
	v_add_f32_e32 v132, v124, v125
	v_sub_f32_e32 v34, v34, v132
	v_pk_fma_f32 v[130:131], v[90:91], v[34:35], v[130:131]
	ds_read_b128 v[88:91], v116 offset:10352
	s_waitcnt lgkmcnt(7)
	v_pk_mul_f32 v[124:125], v[92:93], v[4:5] op_sel:[0,1] op_sel_hi:[1,0]
	v_pk_mul_f32 v[126:127], v[94:95], v[70:71]
	ds_read_b128 v[92:95], v116 offset:10368
	s_waitcnt lgkmcnt(7)
	v_pk_fma_f32 v[124:125], v[96:97], v[74:75], v[124:125]
	v_pk_fma_f32 v[126:127], v[98:99], v[80:81], v[126:127]
	ds_read_b128 v[96:99], v116 offset:10384
	s_waitcnt lgkmcnt(7)
	v_pk_fma_f32 v[124:125], v[100:101], v[78:79], v[124:125]
	v_pk_fma_f32 v[126:127], v[102:103], v[76:77], v[126:127]
	ds_read_b128 v[100:103], v116 offset:10496
	s_waitcnt lgkmcnt(7)
	v_pk_fma_f32 v[124:125], v[104:105], v[72:73], v[124:125]
	v_pk_fma_f32 v[126:127], v[106:107], v[66:67], v[126:127]
	ds_read_b128 v[104:107], v116 offset:10512
	s_waitcnt lgkmcnt(7)
	v_pk_fma_f32 v[124:125], v[108:109], v[64:65], v[124:125]
	v_pk_fma_f32 v[126:127], v[110:111], v[62:63], v[126:127]
	ds_read_b128 v[108:111], v116 offset:10528
	s_waitcnt lgkmcnt(7)
	v_pk_fma_f32 v[124:125], v[112:113], v[60:61], v[124:125]
	v_pk_fma_f32 v[126:127], v[114:115], v[56:57], v[126:127]
	ds_read_b128 v[112:115], v116 offset:10544
	s_waitcnt lgkmcnt(7)
	v_pk_fma_f32 v[124:125], v[84:85], v[54:55], v[124:125]
	v_pk_fma_f32 v[126:127], v[86:87], v[52:53], v[126:127]
	ds_read_b128 v[84:87], v116 offset:10560
	s_waitcnt lgkmcnt(7)
	v_pk_fma_f32 v[124:125], v[88:89], v[48:49], v[124:125]
	v_pk_fma_f32 v[126:127], v[90:91], v[46:47], v[126:127]
	ds_read_b128 v[88:91], v116 offset:10576
	s_waitcnt lgkmcnt(7)
	v_pk_fma_f32 v[124:125], v[92:93], v[42:43], v[124:125]
	v_pk_fma_f32 v[126:127], v[94:95], v[40:41], v[126:127]
	ds_read_b128 v[92:95], v116 offset:10592
	s_waitcnt lgkmcnt(7)
	v_pk_fma_f32 v[124:125], v[96:97], v[36:37], v[124:125]
	v_pk_add_f32 v[128:129], v[128:129], v[130:131]
	v_add_f32_e32 v133, v128, v129
	v_sub_f32_e32 v35, v35, v133
	v_pk_fma_f32 v[126:127], v[98:99], v[34:35], v[126:127]
	ds_read_b128 v[96:99], v116 offset:10608
	s_waitcnt lgkmcnt(7)
	v_pk_mul_f32 v[128:129], v[100:101], v[4:5] op_sel:[0,1] op_sel_hi:[1,0]
	v_pk_mul_f32 v[130:131], v[102:103], v[70:71]
	ds_read_b128 v[100:103], v116 offset:10624
	s_waitcnt lgkmcnt(7)
	v_pk_fma_f32 v[128:129], v[104:105], v[74:75], v[128:129]
	v_pk_fma_f32 v[130:131], v[106:107], v[80:81], v[130:131]
	ds_read_b128 v[104:107], v116 offset:10640
	s_waitcnt lgkmcnt(7)
	v_pk_fma_f32 v[128:129], v[108:109], v[78:79], v[128:129]
	v_pk_fma_f32 v[130:131], v[110:111], v[76:77], v[130:131]
	ds_read_b128 v[108:111], v116 offset:10656
	s_waitcnt lgkmcnt(7)
	v_pk_fma_f32 v[128:129], v[112:113], v[72:73], v[128:129]
	v_pk_fma_f32 v[130:131], v[114:115], v[66:67], v[130:131]
	ds_read_b128 v[112:115], v116 offset:10752
	s_waitcnt lgkmcnt(7)
	v_pk_fma_f32 v[128:129], v[84:85], v[64:65], v[128:129]
	v_pk_fma_f32 v[130:131], v[86:87], v[62:63], v[130:131]
	ds_read_b128 v[84:87], v116 offset:10768
	s_waitcnt lgkmcnt(7)
	v_pk_fma_f32 v[128:129], v[88:89], v[60:61], v[128:129]
	v_pk_fma_f32 v[130:131], v[90:91], v[56:57], v[130:131]
	ds_read_b128 v[88:91], v116 offset:10784
	s_waitcnt lgkmcnt(7)
	v_pk_fma_f32 v[128:129], v[92:93], v[54:55], v[128:129]
	v_pk_fma_f32 v[130:131], v[94:95], v[52:53], v[130:131]
	ds_read_b128 v[92:95], v116 offset:10800
	s_waitcnt lgkmcnt(7)
	v_pk_fma_f32 v[128:129], v[96:97], v[48:49], v[128:129]
	v_pk_fma_f32 v[130:131], v[98:99], v[46:47], v[130:131]
	ds_read_b128 v[96:99], v116 offset:10816
	s_waitcnt lgkmcnt(7)
	v_pk_fma_f32 v[128:129], v[100:101], v[42:43], v[128:129]
	v_pk_fma_f32 v[130:131], v[102:103], v[40:41], v[130:131]
	ds_read_b128 v[100:103], v116 offset:10832
	s_waitcnt lgkmcnt(7)
; __device__ __forceinline__ void gd_prep_item(CArgs* a, LAS unsigned char* lds, int l, int item) {
;     ...
;         for (int t = 1; t < 64; ++t) nrow[t] = NM[t * 64 + lane];
; #pragma unroll
;         for (int t = 1; t < 64; ++t) { float s0 = 0.f, s1 = 0.f;
; #pragma unroll
;             for (int sI = 0; sI < t; ++sI) { const float cf = __builtin_bit_cast(float, __builtin_amdgcn_readlane(__builtin_bit_cast(int, nrow[t]), sI)); if (sI & 1) s1 += cf * x[sI]; else s0 += cf * x[sI]; }
;             x[t] -= s0 + s1; }
	v_pk_fma_f32 v[128:129], v[104:105], v[36:37], v[128:129]
	v_pk_fma_f32 v[130:131], v[106:107], v[34:35], v[130:131]
	ds_read_b128 v[104:107], v116 offset:10848
	v_pk_add_f32 v[124:125], v[124:125], v[126:127]
	v_add_f32_e32 v132, v124, v125
	v_sub_f32_e32 v30, v30, v132
	s_waitcnt lgkmcnt(7)
	v_pk_fma_f32 v[128:129], v[108:109], v[30:31], v[128:129]
	ds_read_b128 v[108:111], v116 offset:10864
	s_waitcnt lgkmcnt(7)
	v_pk_mul_f32 v[124:125], v[112:113], v[4:5] op_sel:[0,1] op_sel_hi:[1,0]
	v_pk_mul_f32 v[126:127], v[114:115], v[70:71]
	ds_read_b128 v[112:115], v116 offset:10880
	s_waitcnt lgkmcnt(7)
	v_pk_fma_f32 v[124:125], v[84:85], v[74:75], v[124:125]
	v_pk_fma_f32 v[126:127], v[86:87], v[80:81], v[126:127]
	ds_read_b128 v[84:87], v116 offset:10896
	s_waitcnt lgkmcnt(7)
	v_pk_fma_f32 v[124:125], v[88:89], v[78:79], v[124:125]
	v_pk_fma_f32 v[126:127], v[90:91], v[76:77], v[126:127]
	ds_read_b128 v[88:91], v116 offset:10912
	s_waitcnt lgkmcnt(7)
	v_pk_fma_f32 v[124:125], v[92:93], v[72:73], v[124:125]
	v_pk_fma_f32 v[126:127], v[94:95], v[66:67], v[126:127]
	ds_read_b128 v[92:95], v116 offset:11008
	s_waitcnt lgkmcnt(7)
	v_pk_fma_f32 v[124:125], v[96:97], v[64:65], v[124:125]
	v_pk_fma_f32 v[126:127], v[98:99], v[62:63], v[126:127]
	ds_read_b128 v[96:99], v116 offset:11024
	s_waitcnt lgkmcnt(7)
	v_pk_fma_f32 v[124:125], v[100:101], v[60:61], v[124:125]
	v_pk_fma_f32 v[126:127], v[102:103], v[56:57], v[126:127]
	ds_read_b128 v[100:103], v116 offset:11040
	s_waitcnt lgkmcnt(7)
	v_pk_fma_f32 v[124:125], v[104:105], v[54:55], v[124:125]
	v_pk_fma_f32 v[126:127], v[106:107], v[52:53], v[126:127]
	ds_read_b128 v[104:107], v116 offset:11056
	s_waitcnt lgkmcnt(7)
	v_pk_fma_f32 v[124:125], v[108:109], v[48:49], v[124:125]
	v_pk_fma_f32 v[126:127], v[110:111], v[46:47], v[126:127]
	ds_read_b128 v[108:111], v116 offset:11072
	s_waitcnt lgkmcnt(7)
	v_pk_fma_f32 v[124:125], v[112:113], v[42:43], v[124:125]
	v_pk_fma_f32 v[126:127], v[114:115], v[40:41], v[126:127]
	ds_read_b128 v[112:115], v116 offset:11088
	s_waitcnt lgkmcnt(7)
	v_pk_fma_f32 v[124:125], v[84:85], v[36:37], v[124:125]
	v_pk_fma_f32 v[126:127], v[86:87], v[34:35], v[126:127]
	ds_read_b128 v[84:87], v116 offset:11104
	v_pk_add_f32 v[128:129], v[128:129], v[130:131]
	v_add_f32_e32 v133, v128, v129
	v_sub_f32_e32 v31, v31, v133
	s_waitcnt lgkmcnt(7)
	v_pk_fma_f32 v[124:125], v[88:89], v[30:31], v[124:125]
	ds_read_b128 v[88:91], v116 offset:11120
	s_waitcnt lgkmcnt(7)
	v_pk_mul_f32 v[128:129], v[92:93], v[4:5] op_sel:[0,1] op_sel_hi:[1,0]
	v_pk_mul_f32 v[130:131], v[94:95], v[70:71]
	ds_read_b128 v[92:95], v116 offset:11136
	s_waitcnt lgkmcnt(7)
	v_pk_fma_f32 v[128:129], v[96:97], v[74:75], v[128:129]
	v_pk_fma_f32 v[130:131], v[98:99], v[80:81], v[130:131]
	ds_read_b128 v[96:99], v116 offset:11152
	s_waitcnt lgkmcnt(7)
	v_pk_fma_f32 v[128:129], v[100:101], v[78:79], v[128:129]
	v_pk_fma_f32 v[130:131], v[102:103], v[76:77], v[130:131]
	ds_read_b128 v[100:103], v116 offset:11168
	s_waitcnt lgkmcnt(7)
	v_pk_fma_f32 v[128:129], v[104:105], v[72:73], v[128:129]
	v_pk_fma_f32 v[130:131], v[106:107], v[66:67], v[130:131]
	ds_read_b128 v[104:107], v116 offset:11264
	s_waitcnt lgkmcnt(7)
	v_pk_fma_f32 v[128:129], v[108:109], v[64:65], v[128:129]
	v_pk_fma_f32 v[130:131], v[110:111], v[62:63], v[130:131]
	ds_read_b128 v[108:111], v116 offset:11280
	s_waitcnt lgkmcnt(7)
	v_pk_fma_f32 v[128:129], v[112:113], v[60:61], v[128:129]
	v_pk_fma_f32 v[130:131], v[114:115], v[56:57], v[130:131]
	ds_read_b128 v[112:115], v116 offset:11296
	s_waitcnt lgkmcnt(7)
	v_pk_fma_f32 v[128:129], v[84:85], v[54:55], v[128:129]
	v_pk_fma_f32 v[130:131], v[86:87], v[52:53], v[130:131]
	ds_read_b128 v[84:87], v116 offset:11312
	s_waitcnt lgkmcnt(7)
	v_pk_fma_f32 v[128:129], v[88:89], v[48:49], v[128:129]
	v_pk_fma_f32 v[130:131], v[90:91], v[46:47], v[130:131]
	ds_read_b128 v[88:91], v116 offset:11328
	s_waitcnt lgkmcnt(7)
	v_pk_fma_f32 v[128:129], v[92:93], v[42:43], v[128:129]
	v_pk_fma_f32 v[130:131], v[94:95], v[40:41], v[130:131]
	ds_read_b128 v[92:95], v116 offset:11344
	s_waitcnt lgkmcnt(7)
	v_pk_fma_f32 v[128:129], v[96:97], v[36:37], v[128:129]
	v_pk_fma_f32 v[130:131], v[98:99], v[34:35], v[130:131]
	ds_read_b128 v[96:99], v116 offset:11360
	s_waitcnt lgkmcnt(7)
	v_pk_fma_f32 v[128:129], v[100:101], v[30:31], v[128:129]
	v_pk_add_f32 v[124:125], v[124:125], v[126:127]
	v_add_f32_e32 v132, v124, v125
	v_sub_f32_e32 v26, v26, v132
	v_pk_fma_f32 v[130:131], v[102:103], v[26:27], v[130:131]
	ds_read_b128 v[100:103], v116 offset:11376
	s_waitcnt lgkmcnt(7)
	v_pk_mul_f32 v[124:125], v[104:105], v[4:5] op_sel:[0,1] op_sel_hi:[1,0]
	v_pk_mul_f32 v[126:127], v[106:107], v[70:71]
	ds_read_b128 v[104:107], v116 offset:11392
	s_waitcnt lgkmcnt(7)
	v_pk_fma_f32 v[124:125], v[108:109], v[74:75], v[124:125]
	v_pk_fma_f32 v[126:127], v[110:111], v[80:81], v[126:127]
	ds_read_b128 v[108:111], v116 offset:11408
	s_waitcnt lgkmcnt(7)
	v_pk_fma_f32 v[124:125], v[112:113], v[78:79], v[124:125]
	v_pk_fma_f32 v[126:127], v[114:115], v[76:77], v[126:127]
	ds_read_b128 v[112:115], v116 offset:11424
	s_waitcnt lgkmcnt(7)
	v_pk_fma_f32 v[124:125], v[84:85], v[72:73], v[124:125]
	v_pk_fma_f32 v[126:127], v[86:87], v[66:67], v[126:127]
	ds_read_b128 v[84:87], v116 offset:11520
	s_waitcnt lgkmcnt(7)
	v_pk_fma_f32 v[124:125], v[88:89], v[64:65], v[124:125]
	v_pk_fma_f32 v[126:127], v[90:91], v[62:63], v[126:127]
	ds_read_b128 v[88:91], v116 offset:11536
	s_waitcnt lgkmcnt(7)
	v_pk_fma_f32 v[124:125], v[92:93], v[60:61], v[124:125]
	v_pk_fma_f32 v[126:127], v[94:95], v[56:57], v[126:127]
	ds_read_b128 v[92:95], v116 offset:11552
	s_waitcnt lgkmcnt(7)
; __device__ __forceinline__ void gd_prep_item(CArgs* a, LAS unsigned char* lds, int l, int item) {
;     ...
;         for (int t = 1; t < 64; ++t) nrow[t] = NM[t * 64 + lane];
; #pragma unroll
;         for (int t = 1; t < 64; ++t) { float s0 = 0.f, s1 = 0.f;
; #pragma unroll
;             for (int sI = 0; sI < t; ++sI) { const float cf = __builtin_bit_cast(float, __builtin_amdgcn_readlane(__builtin_bit_cast(int, nrow[t]), sI)); if (sI & 1) s1 += cf * x[sI]; else s0 += cf * x[sI]; }
;             x[t] -= s0 + s1; }
	v_pk_fma_f32 v[124:125], v[96:97], v[54:55], v[124:125]
	v_pk_fma_f32 v[126:127], v[98:99], v[52:53], v[126:127]
	ds_read_b128 v[96:99], v116 offset:11568
	s_waitcnt lgkmcnt(7)
	v_pk_fma_f32 v[124:125], v[100:101], v[48:49], v[124:125]
	v_pk_fma_f32 v[126:127], v[102:103], v[46:47], v[126:127]
	ds_read_b128 v[100:103], v116 offset:11584
	s_waitcnt lgkmcnt(7)
	v_pk_fma_f32 v[124:125], v[104:105], v[42:43], v[124:125]
	v_pk_fma_f32 v[126:127], v[106:107], v[40:41], v[126:127]
	ds_read_b128 v[104:107], v116 offset:11600
	s_waitcnt lgkmcnt(7)
	v_pk_fma_f32 v[124:125], v[108:109], v[36:37], v[124:125]
	v_pk_fma_f32 v[126:127], v[110:111], v[34:35], v[126:127]
	ds_read_b128 v[108:111], v116 offset:11616
	s_waitcnt lgkmcnt(7)
	v_pk_fma_f32 v[124:125], v[112:113], v[30:31], v[124:125]
	v_pk_add_f32 v[128:129], v[128:129], v[130:131]
	v_add_f32_e32 v133, v128, v129
	v_sub_f32_e32 v27, v27, v133
	v_pk_fma_f32 v[126:127], v[114:115], v[26:27], v[126:127]
	ds_read_b128 v[112:115], v116 offset:11632
	s_waitcnt lgkmcnt(7)
	v_pk_mul_f32 v[128:129], v[84:85], v[4:5] op_sel:[0,1] op_sel_hi:[1,0]
	v_pk_mul_f32 v[130:131], v[86:87], v[70:71]
	ds_read_b128 v[84:87], v116 offset:11648
	s_waitcnt lgkmcnt(7)
	v_pk_fma_f32 v[128:129], v[88:89], v[74:75], v[128:129]
	v_pk_fma_f32 v[130:131], v[90:91], v[80:81], v[130:131]
	ds_read_b128 v[88:91], v116 offset:11664
	s_waitcnt lgkmcnt(7)
	v_pk_fma_f32 v[128:129], v[92:93], v[78:79], v[128:129]
	v_pk_fma_f32 v[130:131], v[94:95], v[76:77], v[130:131]
	ds_read_b128 v[92:95], v116 offset:11680
	s_waitcnt lgkmcnt(7)
	v_pk_fma_f32 v[128:129], v[96:97], v[72:73], v[128:129]
	v_pk_fma_f32 v[130:131], v[98:99], v[66:67], v[130:131]
	ds_read_b128 v[96:99], v116 offset:11696
	s_waitcnt lgkmcnt(7)
	v_pk_fma_f32 v[128:129], v[100:101], v[64:65], v[128:129]
	v_pk_fma_f32 v[130:131], v[102:103], v[62:63], v[130:131]
	ds_read_b128 v[100:103], v116 offset:11776
	s_waitcnt lgkmcnt(7)
	v_pk_fma_f32 v[128:129], v[104:105], v[60:61], v[128:129]
	v_pk_fma_f32 v[130:131], v[106:107], v[56:57], v[130:131]
	ds_read_b128 v[104:107], v116 offset:11792
	s_waitcnt lgkmcnt(7)
	v_pk_fma_f32 v[128:129], v[108:109], v[54:55], v[128:129]
	v_pk_fma_f32 v[130:131], v[110:111], v[52:53], v[130:131]
	ds_read_b128 v[108:111], v116 offset:11808
	s_waitcnt lgkmcnt(7)
	v_pk_fma_f32 v[128:129], v[112:113], v[48:49], v[128:129]
	v_pk_fma_f32 v[130:131], v[114:115], v[46:47], v[130:131]
	ds_read_b128 v[112:115], v116 offset:11824
	s_waitcnt lgkmcnt(7)
	v_pk_fma_f32 v[128:129], v[84:85], v[42:43], v[128:129]
	v_pk_fma_f32 v[130:131], v[86:87], v[40:41], v[130:131]
	ds_read_b128 v[84:87], v116 offset:11840
	s_waitcnt lgkmcnt(7)
	v_pk_fma_f32 v[128:129], v[88:89], v[36:37], v[128:129]
	v_pk_fma_f32 v[130:131], v[90:91], v[34:35], v[130:131]
	ds_read_b128 v[88:91], v116 offset:11856
	s_waitcnt lgkmcnt(7)
	v_pk_fma_f32 v[128:129], v[92:93], v[30:31], v[128:129]
	v_pk_fma_f32 v[130:131], v[94:95], v[26:27], v[130:131]
	ds_read_b128 v[92:95], v116 offset:11872
	v_pk_add_f32 v[124:125], v[124:125], v[126:127]
	v_add_f32_e32 v132, v124, v125
	v_sub_f32_e32 v24, v24, v132
	s_waitcnt lgkmcnt(7)
	v_pk_fma_f32 v[128:129], v[96:97], v[24:25], v[128:129]
	ds_read_b128 v[96:99], v116 offset:11888
	s_waitcnt lgkmcnt(7)
	v_pk_mul_f32 v[124:125], v[100:101], v[4:5] op_sel:[0,1] op_sel_hi:[1,0]
	v_pk_mul_f32 v[126:127], v[102:103], v[70:71]
	ds_read_b128 v[100:103], v116 offset:11904
	s_waitcnt lgkmcnt(7)
	v_pk_fma_f32 v[124:125], v[104:105], v[74:75], v[124:125]
	v_pk_fma_f32 v[126:127], v[106:107], v[80:81], v[126:127]
	ds_read_b128 v[104:107], v116 offset:11920
	s_waitcnt lgkmcnt(7)
	v_pk_fma_f32 v[124:125], v[108:109], v[78:79], v[124:125]
	v_pk_fma_f32 v[126:127], v[110:111], v[76:77], v[126:127]
	ds_read_b128 v[108:111], v116 offset:11936
	s_waitcnt lgkmcnt(7)
	v_pk_fma_f32 v[124:125], v[112:113], v[72:73], v[124:125]
	v_pk_fma_f32 v[126:127], v[114:115], v[66:67], v[126:127]
	ds_read_b128 v[112:115], v116 offset:11952
	s_waitcnt lgkmcnt(7)
	v_pk_fma_f32 v[124:125], v[84:85], v[64:65], v[124:125]
	v_pk_fma_f32 v[126:127], v[86:87], v[62:63], v[126:127]
	ds_read_b128 v[84:87], v116 offset:12032
	s_waitcnt lgkmcnt(7)
	v_pk_fma_f32 v[124:125], v[88:89], v[60:61], v[124:125]
	v_pk_fma_f32 v[126:127], v[90:91], v[56:57], v[126:127]
	ds_read_b128 v[88:91], v116 offset:12048
	s_waitcnt lgkmcnt(7)
	v_pk_fma_f32 v[124:125], v[92:93], v[54:55], v[124:125]
	v_pk_fma_f32 v[126:127], v[94:95], v[52:53], v[126:127]
	ds_read_b128 v[92:95], v116 offset:12064
	s_waitcnt lgkmcnt(7)
	v_pk_fma_f32 v[124:125], v[96:97], v[48:49], v[124:125]
	v_pk_fma_f32 v[126:127], v[98:99], v[46:47], v[126:127]
	ds_read_b128 v[96:99], v116 offset:12080
	s_waitcnt lgkmcnt(7)
	v_pk_fma_f32 v[124:125], v[100:101], v[42:43], v[124:125]
	v_pk_fma_f32 v[126:127], v[102:103], v[40:41], v[126:127]
	ds_read_b128 v[100:103], v116 offset:12096
	s_waitcnt lgkmcnt(7)
	v_pk_fma_f32 v[124:125], v[104:105], v[36:37], v[124:125]
	v_pk_fma_f32 v[126:127], v[106:107], v[34:35], v[126:127]
	ds_read_b128 v[104:107], v116 offset:12112
	s_waitcnt lgkmcnt(7)
	v_pk_fma_f32 v[124:125], v[108:109], v[30:31], v[124:125]
	v_pk_fma_f32 v[126:127], v[110:111], v[26:27], v[126:127]
	ds_read_b128 v[108:111], v116 offset:12128
	v_pk_add_f32 v[128:129], v[128:129], v[130:131]
	v_add_f32_e32 v133, v128, v129
	v_sub_f32_e32 v25, v25, v133
	s_waitcnt lgkmcnt(7)
	v_pk_fma_f32 v[124:125], v[112:113], v[24:25], v[124:125]
	ds_read_b128 v[112:115], v116 offset:12144
	s_waitcnt lgkmcnt(7)
	v_pk_mul_f32 v[128:129], v[84:85], v[4:5] op_sel:[0,1] op_sel_hi:[1,0]
	v_pk_mul_f32 v[130:131], v[86:87], v[70:71]
	ds_read_b128 v[84:87], v116 offset:12160
	s_waitcnt lgkmcnt(7)
; __device__ __forceinline__ void gd_prep_item(CArgs* a, LAS unsigned char* lds, int l, int item) {
;     ...
;         for (int t = 1; t < 64; ++t) nrow[t] = NM[t * 64 + lane];
; #pragma unroll
;         for (int t = 1; t < 64; ++t) { float s0 = 0.f, s1 = 0.f;
; #pragma unroll
;             for (int sI = 0; sI < t; ++sI) { const float cf = __builtin_bit_cast(float, __builtin_amdgcn_readlane(__builtin_bit_cast(int, nrow[t]), sI)); if (sI & 1) s1 += cf * x[sI]; else s0 += cf * x[sI]; }
;             x[t] -= s0 + s1; }
	v_pk_fma_f32 v[128:129], v[88:89], v[74:75], v[128:129]
	v_pk_fma_f32 v[130:131], v[90:91], v[80:81], v[130:131]
	ds_read_b128 v[88:91], v116 offset:12176
	s_waitcnt lgkmcnt(7)
	v_pk_fma_f32 v[128:129], v[92:93], v[78:79], v[128:129]
	v_pk_fma_f32 v[130:131], v[94:95], v[76:77], v[130:131]
	ds_read_b128 v[92:95], v116 offset:12192
	s_waitcnt lgkmcnt(7)
	v_pk_fma_f32 v[128:129], v[96:97], v[72:73], v[128:129]
	v_pk_fma_f32 v[130:131], v[98:99], v[66:67], v[130:131]
	ds_read_b128 v[96:99], v116 offset:12208
	s_waitcnt lgkmcnt(7)
	v_pk_fma_f32 v[128:129], v[100:101], v[64:65], v[128:129]
	v_pk_fma_f32 v[130:131], v[102:103], v[62:63], v[130:131]
	ds_read_b128 v[100:103], v116 offset:12288
	s_waitcnt lgkmcnt(7)
	v_pk_fma_f32 v[128:129], v[104:105], v[60:61], v[128:129]
	v_pk_fma_f32 v[130:131], v[106:107], v[56:57], v[130:131]
	ds_read_b128 v[104:107], v116 offset:12304
	s_waitcnt lgkmcnt(7)
	v_pk_fma_f32 v[128:129], v[108:109], v[54:55], v[128:129]
	v_pk_fma_f32 v[130:131], v[110:111], v[52:53], v[130:131]
	ds_read_b128 v[108:111], v116 offset:12320
	s_waitcnt lgkmcnt(7)
	v_pk_fma_f32 v[128:129], v[112:113], v[48:49], v[128:129]
	v_pk_fma_f32 v[130:131], v[114:115], v[46:47], v[130:131]
	ds_read_b128 v[112:115], v116 offset:12336
	s_waitcnt lgkmcnt(7)
	v_pk_fma_f32 v[128:129], v[84:85], v[42:43], v[128:129]
	v_pk_fma_f32 v[130:131], v[86:87], v[40:41], v[130:131]
	ds_read_b128 v[84:87], v116 offset:12352
	s_waitcnt lgkmcnt(7)
	v_pk_fma_f32 v[128:129], v[88:89], v[36:37], v[128:129]
	v_pk_fma_f32 v[130:131], v[90:91], v[34:35], v[130:131]
	ds_read_b128 v[88:91], v116 offset:12368
	s_waitcnt lgkmcnt(7)
	v_pk_fma_f32 v[128:129], v[92:93], v[30:31], v[128:129]
	v_pk_fma_f32 v[130:131], v[94:95], v[26:27], v[130:131]
	ds_read_b128 v[92:95], v116 offset:12384
	s_waitcnt lgkmcnt(7)
	v_pk_fma_f32 v[128:129], v[96:97], v[24:25], v[128:129]
	v_pk_add_f32 v[124:125], v[124:125], v[126:127]
	v_add_f32_e32 v132, v124, v125
	v_sub_f32_e32 v20, v20, v132
	v_pk_fma_f32 v[130:131], v[98:99], v[20:21], v[130:131]
	ds_read_b128 v[96:99], v116 offset:12400
	s_waitcnt lgkmcnt(7)
	v_pk_mul_f32 v[124:125], v[100:101], v[4:5] op_sel:[0,1] op_sel_hi:[1,0]
	v_pk_mul_f32 v[126:127], v[102:103], v[70:71]
	ds_read_b128 v[100:103], v116 offset:12416
	s_waitcnt lgkmcnt(7)
	v_pk_fma_f32 v[124:125], v[104:105], v[74:75], v[124:125]
	v_pk_fma_f32 v[126:127], v[106:107], v[80:81], v[126:127]
	ds_read_b128 v[104:107], v116 offset:12432
	s_waitcnt lgkmcnt(7)
	v_pk_fma_f32 v[124:125], v[108:109], v[78:79], v[124:125]
	v_pk_fma_f32 v[126:127], v[110:111], v[76:77], v[126:127]
	ds_read_b128 v[108:111], v116 offset:12448
	s_waitcnt lgkmcnt(7)
	v_pk_fma_f32 v[124:125], v[112:113], v[72:73], v[124:125]
	v_pk_fma_f32 v[126:127], v[114:115], v[66:67], v[126:127]
	ds_read_b128 v[112:115], v116 offset:12464
	s_waitcnt lgkmcnt(7)
	v_pk_fma_f32 v[124:125], v[84:85], v[64:65], v[124:125]
	v_pk_fma_f32 v[126:127], v[86:87], v[62:63], v[126:127]
	ds_read_b128 v[84:87], v116 offset:12544
	s_waitcnt lgkmcnt(7)
	v_pk_fma_f32 v[124:125], v[88:89], v[60:61], v[124:125]
	v_pk_fma_f32 v[126:127], v[90:91], v[56:57], v[126:127]
	ds_read_b128 v[88:91], v116 offset:12560
	s_waitcnt lgkmcnt(7)
	v_pk_fma_f32 v[124:125], v[92:93], v[54:55], v[124:125]
	v_pk_fma_f32 v[126:127], v[94:95], v[52:53], v[126:127]
	ds_read_b128 v[92:95], v116 offset:12576
	s_waitcnt lgkmcnt(7)
	v_pk_fma_f32 v[124:125], v[96:97], v[48:49], v[124:125]
	v_pk_fma_f32 v[126:127], v[98:99], v[46:47], v[126:127]
	ds_read_b128 v[96:99], v116 offset:12592
	s_waitcnt lgkmcnt(7)
	v_pk_fma_f32 v[124:125], v[100:101], v[42:43], v[124:125]
	v_pk_fma_f32 v[126:127], v[102:103], v[40:41], v[126:127]
	ds_read_b128 v[100:103], v116 offset:12608
	s_waitcnt lgkmcnt(7)
	v_pk_fma_f32 v[124:125], v[104:105], v[36:37], v[124:125]
	v_pk_fma_f32 v[126:127], v[106:107], v[34:35], v[126:127]
	ds_read_b128 v[104:107], v116 offset:12624
	s_waitcnt lgkmcnt(7)
	v_pk_fma_f32 v[124:125], v[108:109], v[30:31], v[124:125]
	v_pk_fma_f32 v[126:127], v[110:111], v[26:27], v[126:127]
	ds_read_b128 v[108:111], v116 offset:12640
	s_waitcnt lgkmcnt(7)
	v_pk_fma_f32 v[124:125], v[112:113], v[24:25], v[124:125]
	v_pk_add_f32 v[128:129], v[128:129], v[130:131]
	v_add_f32_e32 v133, v128, v129
	v_sub_f32_e32 v21, v21, v133
	v_pk_fma_f32 v[126:127], v[114:115], v[20:21], v[126:127]
	ds_read_b128 v[112:115], v116 offset:12656
	s_waitcnt lgkmcnt(7)
	v_pk_mul_f32 v[128:129], v[84:85], v[4:5] op_sel:[0,1] op_sel_hi:[1,0]
	v_pk_mul_f32 v[130:131], v[86:87], v[70:71]
	ds_read_b128 v[84:87], v116 offset:12672
	s_waitcnt lgkmcnt(7)
	v_pk_fma_f32 v[128:129], v[88:89], v[74:75], v[128:129]
	v_pk_fma_f32 v[130:131], v[90:91], v[80:81], v[130:131]
	ds_read_b128 v[88:91], v116 offset:12688
	s_waitcnt lgkmcnt(7)
	v_pk_fma_f32 v[128:129], v[92:93], v[78:79], v[128:129]
	v_pk_fma_f32 v[130:131], v[94:95], v[76:77], v[130:131]
	ds_read_b128 v[92:95], v116 offset:12704
	s_waitcnt lgkmcnt(7)
	v_pk_fma_f32 v[128:129], v[96:97], v[72:73], v[128:129]
	v_pk_fma_f32 v[130:131], v[98:99], v[66:67], v[130:131]
	ds_read_b128 v[96:99], v116 offset:12720
	s_waitcnt lgkmcnt(7)
	v_pk_fma_f32 v[128:129], v[100:101], v[64:65], v[128:129]
	v_pk_fma_f32 v[130:131], v[102:103], v[62:63], v[130:131]
	ds_read_b128 v[100:103], v116 offset:12736
	s_waitcnt lgkmcnt(7)
	v_pk_fma_f32 v[128:129], v[104:105], v[60:61], v[128:129]
	v_pk_fma_f32 v[130:131], v[106:107], v[56:57], v[130:131]
	ds_read_b128 v[104:107], v116 offset:12800
	s_waitcnt lgkmcnt(7)
	v_pk_fma_f32 v[128:129], v[108:109], v[54:55], v[128:129]
	v_pk_fma_f32 v[130:131], v[110:111], v[52:53], v[130:131]
	ds_read_b128 v[108:111], v116 offset:12816
	s_waitcnt lgkmcnt(7)
; __device__ __forceinline__ void gd_prep_item(CArgs* a, LAS unsigned char* lds, int l, int item) {
;     ...
;         for (int t = 1; t < 64; ++t) nrow[t] = NM[t * 64 + lane];
; #pragma unroll
;         for (int t = 1; t < 64; ++t) { float s0 = 0.f, s1 = 0.f;
; #pragma unroll
;             for (int sI = 0; sI < t; ++sI) { const float cf = __builtin_bit_cast(float, __builtin_amdgcn_readlane(__builtin_bit_cast(int, nrow[t]), sI)); if (sI & 1) s1 += cf * x[sI]; else s0 += cf * x[sI]; }
;             x[t] -= s0 + s1; }
	v_pk_fma_f32 v[128:129], v[112:113], v[48:49], v[128:129]
	v_pk_fma_f32 v[130:131], v[114:115], v[46:47], v[130:131]
	ds_read_b128 v[112:115], v116 offset:12832
	s_waitcnt lgkmcnt(7)
	v_pk_fma_f32 v[128:129], v[84:85], v[42:43], v[128:129]
	v_pk_fma_f32 v[130:131], v[86:87], v[40:41], v[130:131]
	ds_read_b128 v[84:87], v116 offset:12848
	s_waitcnt lgkmcnt(7)
	v_pk_fma_f32 v[128:129], v[88:89], v[36:37], v[128:129]
	v_pk_fma_f32 v[130:131], v[90:91], v[34:35], v[130:131]
	ds_read_b128 v[88:91], v116 offset:12864
	s_waitcnt lgkmcnt(7)
	v_pk_fma_f32 v[128:129], v[92:93], v[30:31], v[128:129]
	v_pk_fma_f32 v[130:131], v[94:95], v[26:27], v[130:131]
	ds_read_b128 v[92:95], v116 offset:12880
	s_waitcnt lgkmcnt(7)
	v_pk_fma_f32 v[128:129], v[96:97], v[24:25], v[128:129]
	v_pk_fma_f32 v[130:131], v[98:99], v[20:21], v[130:131]
	ds_read_b128 v[96:99], v116 offset:12896
	v_pk_add_f32 v[124:125], v[124:125], v[126:127]
	v_add_f32_e32 v132, v124, v125
	v_sub_f32_e32 v18, v18, v132
	s_waitcnt lgkmcnt(7)
	v_pk_fma_f32 v[128:129], v[100:101], v[18:19], v[128:129]
	ds_read_b128 v[100:103], v116 offset:12912
	s_waitcnt lgkmcnt(7)
	v_pk_mul_f32 v[124:125], v[104:105], v[4:5] op_sel:[0,1] op_sel_hi:[1,0]
	v_pk_mul_f32 v[126:127], v[106:107], v[70:71]
	ds_read_b128 v[104:107], v116 offset:12928
	s_waitcnt lgkmcnt(7)
	v_pk_fma_f32 v[124:125], v[108:109], v[74:75], v[124:125]
	v_pk_fma_f32 v[126:127], v[110:111], v[80:81], v[126:127]
	ds_read_b128 v[108:111], v116 offset:12944
	s_waitcnt lgkmcnt(7)
	v_pk_fma_f32 v[124:125], v[112:113], v[78:79], v[124:125]
	v_pk_fma_f32 v[126:127], v[114:115], v[76:77], v[126:127]
	ds_read_b128 v[112:115], v116 offset:12960
	s_waitcnt lgkmcnt(7)
	v_pk_fma_f32 v[124:125], v[84:85], v[72:73], v[124:125]
	v_pk_fma_f32 v[126:127], v[86:87], v[66:67], v[126:127]
	ds_read_b128 v[84:87], v116 offset:12976
	s_waitcnt lgkmcnt(7)
	v_pk_fma_f32 v[124:125], v[88:89], v[64:65], v[124:125]
	v_pk_fma_f32 v[126:127], v[90:91], v[62:63], v[126:127]
	ds_read_b128 v[88:91], v116 offset:12992
	s_waitcnt lgkmcnt(7)
	v_pk_fma_f32 v[124:125], v[92:93], v[60:61], v[124:125]
	v_pk_fma_f32 v[126:127], v[94:95], v[56:57], v[126:127]
	ds_read_b128 v[92:95], v116 offset:13056
	s_waitcnt lgkmcnt(7)
	v_pk_fma_f32 v[124:125], v[96:97], v[54:55], v[124:125]
	v_pk_fma_f32 v[126:127], v[98:99], v[52:53], v[126:127]
	ds_read_b128 v[96:99], v116 offset:13072
	s_waitcnt lgkmcnt(7)
	v_pk_fma_f32 v[124:125], v[100:101], v[48:49], v[124:125]
	v_pk_fma_f32 v[126:127], v[102:103], v[46:47], v[126:127]
	ds_read_b128 v[100:103], v116 offset:13088
	s_waitcnt lgkmcnt(7)
	v_pk_fma_f32 v[124:125], v[104:105], v[42:43], v[124:125]
	v_pk_fma_f32 v[126:127], v[106:107], v[40:41], v[126:127]
	ds_read_b128 v[104:107], v116 offset:13104
	s_waitcnt lgkmcnt(7)
	v_pk_fma_f32 v[124:125], v[108:109], v[36:37], v[124:125]
	v_pk_fma_f32 v[126:127], v[110:111], v[34:35], v[126:127]
	ds_read_b128 v[108:111], v116 offset:13120
	s_waitcnt lgkmcnt(7)
	v_pk_fma_f32 v[124:125], v[112:113], v[30:31], v[124:125]
	v_pk_fma_f32 v[126:127], v[114:115], v[26:27], v[126:127]
	ds_read_b128 v[112:115], v116 offset:13136
	s_waitcnt lgkmcnt(7)
	v_pk_fma_f32 v[124:125], v[84:85], v[24:25], v[124:125]
	v_pk_fma_f32 v[126:127], v[86:87], v[20:21], v[126:127]
	ds_read_b128 v[84:87], v116 offset:13152
	v_pk_add_f32 v[128:129], v[128:129], v[130:131]
	v_add_f32_e32 v133, v128, v129
	v_sub_f32_e32 v19, v19, v133
	s_waitcnt lgkmcnt(7)
	v_pk_fma_f32 v[124:125], v[88:89], v[18:19], v[124:125]
	ds_read_b128 v[88:91], v116 offset:13168
	s_waitcnt lgkmcnt(7)
	v_pk_mul_f32 v[128:129], v[92:93], v[4:5] op_sel:[0,1] op_sel_hi:[1,0]
	v_pk_mul_f32 v[130:131], v[94:95], v[70:71]
	ds_read_b128 v[92:95], v116 offset:13184
	s_waitcnt lgkmcnt(7)
	v_pk_fma_f32 v[128:129], v[96:97], v[74:75], v[128:129]
	v_pk_fma_f32 v[130:131], v[98:99], v[80:81], v[130:131]
	ds_read_b128 v[96:99], v116 offset:13200
	s_waitcnt lgkmcnt(7)
	v_pk_fma_f32 v[128:129], v[100:101], v[78:79], v[128:129]
	v_pk_fma_f32 v[130:131], v[102:103], v[76:77], v[130:131]
	ds_read_b128 v[100:103], v116 offset:13216
	s_waitcnt lgkmcnt(7)
	v_pk_fma_f32 v[128:129], v[104:105], v[72:73], v[128:129]
	v_pk_fma_f32 v[130:131], v[106:107], v[66:67], v[130:131]
	ds_read_b128 v[104:107], v116 offset:13232
	s_waitcnt lgkmcnt(7)
	v_pk_fma_f32 v[128:129], v[108:109], v[64:65], v[128:129]
	v_pk_fma_f32 v[130:131], v[110:111], v[62:63], v[130:131]
	ds_read_b128 v[108:111], v116 offset:13248
	s_waitcnt lgkmcnt(7)
	v_pk_fma_f32 v[128:129], v[112:113], v[60:61], v[128:129]
	v_pk_fma_f32 v[130:131], v[114:115], v[56:57], v[130:131]
	ds_read_b128 v[112:115], v116 offset:13312
	s_waitcnt lgkmcnt(7)
	v_pk_fma_f32 v[128:129], v[84:85], v[54:55], v[128:129]
	v_pk_fma_f32 v[130:131], v[86:87], v[52:53], v[130:131]
	ds_read_b128 v[84:87], v116 offset:13328
	s_waitcnt lgkmcnt(7)
	v_pk_fma_f32 v[128:129], v[88:89], v[48:49], v[128:129]
	v_pk_fma_f32 v[130:131], v[90:91], v[46:47], v[130:131]
	ds_read_b128 v[88:91], v116 offset:13344
	s_waitcnt lgkmcnt(7)
	v_pk_fma_f32 v[128:129], v[92:93], v[42:43], v[128:129]
	v_pk_fma_f32 v[130:131], v[94:95], v[40:41], v[130:131]
	ds_read_b128 v[92:95], v116 offset:13360
	s_waitcnt lgkmcnt(7)
	v_pk_fma_f32 v[128:129], v[96:97], v[36:37], v[128:129]
	v_pk_fma_f32 v[130:131], v[98:99], v[34:35], v[130:131]
	ds_read_b128 v[96:99], v116 offset:13376
	s_waitcnt lgkmcnt(7)
	v_pk_fma_f32 v[128:129], v[100:101], v[30:31], v[128:129]
	v_pk_fma_f32 v[130:131], v[102:103], v[26:27], v[130:131]
	ds_read_b128 v[100:103], v116 offset:13392
	s_waitcnt lgkmcnt(7)
	v_pk_fma_f32 v[128:129], v[104:105], v[24:25], v[128:129]
	v_pk_fma_f32 v[130:131], v[106:107], v[20:21], v[130:131]
	ds_read_b128 v[104:107], v116 offset:13408
	s_waitcnt lgkmcnt(7)
; __device__ __forceinline__ void gd_prep_item(CArgs* a, LAS unsigned char* lds, int l, int item) {
;     ...
;         for (int t = 1; t < 64; ++t) nrow[t] = NM[t * 64 + lane];
; #pragma unroll
;         for (int t = 1; t < 64; ++t) { float s0 = 0.f, s1 = 0.f;
; #pragma unroll
;             for (int sI = 0; sI < t; ++sI) { const float cf = __builtin_bit_cast(float, __builtin_amdgcn_readlane(__builtin_bit_cast(int, nrow[t]), sI)); if (sI & 1) s1 += cf * x[sI]; else s0 += cf * x[sI]; }
;             x[t] -= s0 + s1; }
	v_pk_fma_f32 v[128:129], v[108:109], v[18:19], v[128:129]
	v_pk_add_f32 v[124:125], v[124:125], v[126:127]
	v_add_f32_e32 v132, v124, v125
	v_sub_f32_e32 v14, v14, v132
	v_pk_fma_f32 v[130:131], v[110:111], v[14:15], v[130:131]
	ds_read_b128 v[108:111], v116 offset:13424
	s_waitcnt lgkmcnt(7)
	v_pk_mul_f32 v[124:125], v[112:113], v[4:5] op_sel:[0,1] op_sel_hi:[1,0]
	v_pk_mul_f32 v[126:127], v[114:115], v[70:71]
	ds_read_b128 v[112:115], v116 offset:13440
	s_waitcnt lgkmcnt(7)
	v_pk_fma_f32 v[124:125], v[84:85], v[74:75], v[124:125]
	v_pk_fma_f32 v[126:127], v[86:87], v[80:81], v[126:127]
	ds_read_b128 v[84:87], v116 offset:13456
	s_waitcnt lgkmcnt(7)
	v_pk_fma_f32 v[124:125], v[88:89], v[78:79], v[124:125]
	v_pk_fma_f32 v[126:127], v[90:91], v[76:77], v[126:127]
	ds_read_b128 v[88:91], v116 offset:13472
	s_waitcnt lgkmcnt(7)
	v_pk_fma_f32 v[124:125], v[92:93], v[72:73], v[124:125]
	v_pk_fma_f32 v[126:127], v[94:95], v[66:67], v[126:127]
	ds_read_b128 v[92:95], v116 offset:13488
	s_waitcnt lgkmcnt(7)
	v_pk_fma_f32 v[124:125], v[96:97], v[64:65], v[124:125]
	v_pk_fma_f32 v[126:127], v[98:99], v[62:63], v[126:127]
	ds_read_b128 v[96:99], v116 offset:13504
	s_waitcnt lgkmcnt(7)
	v_pk_fma_f32 v[124:125], v[100:101], v[60:61], v[124:125]
	v_pk_fma_f32 v[126:127], v[102:103], v[56:57], v[126:127]
	ds_read_b128 v[100:103], v116 offset:13568
	s_waitcnt lgkmcnt(7)
	v_pk_fma_f32 v[124:125], v[104:105], v[54:55], v[124:125]
	v_pk_fma_f32 v[126:127], v[106:107], v[52:53], v[126:127]
	ds_read_b128 v[104:107], v116 offset:13584
	s_waitcnt lgkmcnt(7)
	v_pk_fma_f32 v[124:125], v[108:109], v[48:49], v[124:125]
	v_pk_fma_f32 v[126:127], v[110:111], v[46:47], v[126:127]
	ds_read_b128 v[108:111], v116 offset:13600
	s_waitcnt lgkmcnt(7)
	v_pk_fma_f32 v[124:125], v[112:113], v[42:43], v[124:125]
	v_pk_fma_f32 v[126:127], v[114:115], v[40:41], v[126:127]
	ds_read_b128 v[112:115], v116 offset:13616
	s_waitcnt lgkmcnt(7)
	v_pk_fma_f32 v[124:125], v[84:85], v[36:37], v[124:125]
	v_pk_fma_f32 v[126:127], v[86:87], v[34:35], v[126:127]
	ds_read_b128 v[84:87], v116 offset:13632
	s_waitcnt lgkmcnt(7)
	v_pk_fma_f32 v[124:125], v[88:89], v[30:31], v[124:125]
	v_pk_fma_f32 v[126:127], v[90:91], v[26:27], v[126:127]
	ds_read_b128 v[88:91], v116 offset:13648
	s_waitcnt lgkmcnt(7)
	v_pk_fma_f32 v[124:125], v[92:93], v[24:25], v[124:125]
	v_pk_fma_f32 v[126:127], v[94:95], v[20:21], v[126:127]
	ds_read_b128 v[92:95], v116 offset:13664
	s_waitcnt lgkmcnt(7)
	v_pk_fma_f32 v[124:125], v[96:97], v[18:19], v[124:125]
	v_pk_add_f32 v[128:129], v[128:129], v[130:131]
	v_add_f32_e32 v133, v128, v129
	v_sub_f32_e32 v15, v15, v133
	v_pk_fma_f32 v[126:127], v[98:99], v[14:15], v[126:127]
	ds_read_b128 v[96:99], v116 offset:13680
	s_waitcnt lgkmcnt(7)
	v_pk_mul_f32 v[128:129], v[100:101], v[4:5] op_sel:[0,1] op_sel_hi:[1,0]
	v_pk_mul_f32 v[130:131], v[102:103], v[70:71]
	ds_read_b128 v[100:103], v116 offset:13696
	s_waitcnt lgkmcnt(7)
	v_pk_fma_f32 v[128:129], v[104:105], v[74:75], v[128:129]
	v_pk_fma_f32 v[130:131], v[106:107], v[80:81], v[130:131]
	ds_read_b128 v[104:107], v116 offset:13712
	s_waitcnt lgkmcnt(7)
	v_pk_fma_f32 v[128:129], v[108:109], v[78:79], v[128:129]
	v_pk_fma_f32 v[130:131], v[110:111], v[76:77], v[130:131]
	ds_read_b128 v[108:111], v116 offset:13728
	s_waitcnt lgkmcnt(7)
	v_pk_fma_f32 v[128:129], v[112:113], v[72:73], v[128:129]
	v_pk_fma_f32 v[130:131], v[114:115], v[66:67], v[130:131]
	ds_read_b128 v[112:115], v116 offset:13744
	s_waitcnt lgkmcnt(7)
	v_pk_fma_f32 v[128:129], v[84:85], v[64:65], v[128:129]
	v_pk_fma_f32 v[130:131], v[86:87], v[62:63], v[130:131]
	ds_read_b128 v[84:87], v116 offset:13760
	s_waitcnt lgkmcnt(7)
	v_pk_fma_f32 v[128:129], v[88:89], v[60:61], v[128:129]
	v_pk_fma_f32 v[130:131], v[90:91], v[56:57], v[130:131]
	ds_read_b128 v[88:91], v116 offset:13776
	s_waitcnt lgkmcnt(7)
	v_pk_fma_f32 v[128:129], v[92:93], v[54:55], v[128:129]
	v_pk_fma_f32 v[130:131], v[94:95], v[52:53], v[130:131]
	ds_read_b128 v[92:95], v116 offset:13824
	s_waitcnt lgkmcnt(7)
	v_pk_fma_f32 v[128:129], v[96:97], v[48:49], v[128:129]
	v_pk_fma_f32 v[130:131], v[98:99], v[46:47], v[130:131]
	ds_read_b128 v[96:99], v116 offset:13840
	s_waitcnt lgkmcnt(7)
	v_pk_fma_f32 v[128:129], v[100:101], v[42:43], v[128:129]
	v_pk_fma_f32 v[130:131], v[102:103], v[40:41], v[130:131]
	ds_read_b128 v[100:103], v116 offset:13856
	s_waitcnt lgkmcnt(7)
	v_pk_fma_f32 v[128:129], v[104:105], v[36:37], v[128:129]
	v_pk_fma_f32 v[130:131], v[106:107], v[34:35], v[130:131]
	ds_read_b128 v[104:107], v116 offset:13872
	s_waitcnt lgkmcnt(7)
	v_pk_fma_f32 v[128:129], v[108:109], v[30:31], v[128:129]
	v_pk_fma_f32 v[130:131], v[110:111], v[26:27], v[130:131]
	ds_read_b128 v[108:111], v116 offset:13888
	s_waitcnt lgkmcnt(7)
	v_pk_fma_f32 v[128:129], v[112:113], v[24:25], v[128:129]
	v_pk_fma_f32 v[130:131], v[114:115], v[20:21], v[130:131]
	ds_read_b128 v[112:115], v116 offset:13904
	s_waitcnt lgkmcnt(7)
	v_pk_fma_f32 v[128:129], v[84:85], v[18:19], v[128:129]
	v_pk_fma_f32 v[130:131], v[86:87], v[14:15], v[130:131]
	ds_read_b128 v[84:87], v116 offset:13920
	v_pk_add_f32 v[124:125], v[124:125], v[126:127]
	v_add_f32_e32 v132, v124, v125
	v_sub_f32_e32 v10, v10, v132
	s_waitcnt lgkmcnt(7)
	v_pk_fma_f32 v[128:129], v[88:89], v[10:11], v[128:129]
	ds_read_b128 v[88:91], v116 offset:13936
	s_waitcnt lgkmcnt(7)
	v_pk_mul_f32 v[124:125], v[92:93], v[4:5] op_sel:[0,1] op_sel_hi:[1,0]
	v_pk_mul_f32 v[126:127], v[94:95], v[70:71]
	ds_read_b128 v[92:95], v116 offset:13952
	s_waitcnt lgkmcnt(7)
	v_pk_fma_f32 v[124:125], v[96:97], v[74:75], v[124:125]
	v_pk_fma_f32 v[126:127], v[98:99], v[80:81], v[126:127]
	ds_read_b128 v[96:99], v116 offset:13968
	s_waitcnt lgkmcnt(7)
; __device__ __forceinline__ void gd_prep_item(CArgs* a, LAS unsigned char* lds, int l, int item) {
;     ...
;         for (int t = 1; t < 64; ++t) nrow[t] = NM[t * 64 + lane];
; #pragma unroll
;         for (int t = 1; t < 64; ++t) { float s0 = 0.f, s1 = 0.f;
; #pragma unroll
;             for (int sI = 0; sI < t; ++sI) { const float cf = __builtin_bit_cast(float, __builtin_amdgcn_readlane(__builtin_bit_cast(int, nrow[t]), sI)); if (sI & 1) s1 += cf * x[sI]; else s0 += cf * x[sI]; }
;             x[t] -= s0 + s1; }
	v_pk_fma_f32 v[124:125], v[100:101], v[78:79], v[124:125]
	v_pk_fma_f32 v[126:127], v[102:103], v[76:77], v[126:127]
	ds_read_b128 v[100:103], v116 offset:13984
	s_waitcnt lgkmcnt(7)
	v_pk_fma_f32 v[124:125], v[104:105], v[72:73], v[124:125]
	v_pk_fma_f32 v[126:127], v[106:107], v[66:67], v[126:127]
	ds_read_b128 v[104:107], v116 offset:14000
	s_waitcnt lgkmcnt(7)
	v_pk_fma_f32 v[124:125], v[108:109], v[64:65], v[124:125]
	v_pk_fma_f32 v[126:127], v[110:111], v[62:63], v[126:127]
	ds_read_b128 v[108:111], v116 offset:14016
	s_waitcnt lgkmcnt(7)
	v_pk_fma_f32 v[124:125], v[112:113], v[60:61], v[124:125]
	v_pk_fma_f32 v[126:127], v[114:115], v[56:57], v[126:127]
	ds_read_b128 v[112:115], v116 offset:14032
	s_waitcnt lgkmcnt(7)
	v_pk_fma_f32 v[124:125], v[84:85], v[54:55], v[124:125]
	v_pk_fma_f32 v[126:127], v[86:87], v[52:53], v[126:127]
	ds_read_b128 v[84:87], v116 offset:14080
	s_waitcnt lgkmcnt(7)
	v_pk_fma_f32 v[124:125], v[88:89], v[48:49], v[124:125]
	v_pk_fma_f32 v[126:127], v[90:91], v[46:47], v[126:127]
	ds_read_b128 v[88:91], v116 offset:14096
	s_waitcnt lgkmcnt(7)
	v_pk_fma_f32 v[124:125], v[92:93], v[42:43], v[124:125]
	v_pk_fma_f32 v[126:127], v[94:95], v[40:41], v[126:127]
	ds_read_b128 v[92:95], v116 offset:14112
	s_waitcnt lgkmcnt(7)
	v_pk_fma_f32 v[124:125], v[96:97], v[36:37], v[124:125]
	v_pk_fma_f32 v[126:127], v[98:99], v[34:35], v[126:127]
	ds_read_b128 v[96:99], v116 offset:14128
	s_waitcnt lgkmcnt(7)
	v_pk_fma_f32 v[124:125], v[100:101], v[30:31], v[124:125]
	v_pk_fma_f32 v[126:127], v[102:103], v[26:27], v[126:127]
	ds_read_b128 v[100:103], v116 offset:14144
	s_waitcnt lgkmcnt(7)
	v_pk_fma_f32 v[124:125], v[104:105], v[24:25], v[124:125]
	v_pk_fma_f32 v[126:127], v[106:107], v[20:21], v[126:127]
	ds_read_b128 v[104:107], v116 offset:14160
	s_waitcnt lgkmcnt(7)
	v_pk_fma_f32 v[124:125], v[108:109], v[18:19], v[124:125]
	v_pk_fma_f32 v[126:127], v[110:111], v[14:15], v[126:127]
	ds_read_b128 v[108:111], v116 offset:14176
	v_pk_add_f32 v[128:129], v[128:129], v[130:131]
	v_add_f32_e32 v133, v128, v129
	v_sub_f32_e32 v11, v11, v133
	s_waitcnt lgkmcnt(7)
	v_pk_fma_f32 v[124:125], v[112:113], v[10:11], v[124:125]
	ds_read_b128 v[112:115], v116 offset:14192
	s_waitcnt lgkmcnt(7)
	v_pk_mul_f32 v[128:129], v[84:85], v[4:5] op_sel:[0,1] op_sel_hi:[1,0]
	v_pk_mul_f32 v[130:131], v[86:87], v[70:71]
	ds_read_b128 v[84:87], v116 offset:14208
	s_waitcnt lgkmcnt(7)
	v_pk_fma_f32 v[128:129], v[88:89], v[74:75], v[128:129]
	v_pk_fma_f32 v[130:131], v[90:91], v[80:81], v[130:131]
	ds_read_b128 v[88:91], v116 offset:14224
	s_waitcnt lgkmcnt(7)
	v_pk_fma_f32 v[128:129], v[92:93], v[78:79], v[128:129]
	v_pk_fma_f32 v[130:131], v[94:95], v[76:77], v[130:131]
	ds_read_b128 v[92:95], v116 offset:14240
	s_waitcnt lgkmcnt(7)
	v_pk_fma_f32 v[128:129], v[96:97], v[72:73], v[128:129]
	v_pk_fma_f32 v[130:131], v[98:99], v[66:67], v[130:131]
	ds_read_b128 v[96:99], v116 offset:14256
	s_waitcnt lgkmcnt(7)
	v_pk_fma_f32 v[128:129], v[100:101], v[64:65], v[128:129]
	v_pk_fma_f32 v[130:131], v[102:103], v[62:63], v[130:131]
	ds_read_b128 v[100:103], v116 offset:14272
	s_waitcnt lgkmcnt(7)
	v_pk_fma_f32 v[128:129], v[104:105], v[60:61], v[128:129]
	v_pk_fma_f32 v[130:131], v[106:107], v[56:57], v[130:131]
	ds_read_b128 v[104:107], v116 offset:14288
	s_waitcnt lgkmcnt(7)
	v_pk_fma_f32 v[128:129], v[108:109], v[54:55], v[128:129]
	v_pk_fma_f32 v[130:131], v[110:111], v[52:53], v[130:131]
	ds_read_b128 v[108:111], v116 offset:14336
	s_waitcnt lgkmcnt(7)
	v_pk_fma_f32 v[128:129], v[112:113], v[48:49], v[128:129]
	v_pk_fma_f32 v[130:131], v[114:115], v[46:47], v[130:131]
	ds_read_b128 v[112:115], v116 offset:14352
	s_waitcnt lgkmcnt(7)
	v_pk_fma_f32 v[128:129], v[84:85], v[42:43], v[128:129]
	v_pk_fma_f32 v[130:131], v[86:87], v[40:41], v[130:131]
	ds_read_b128 v[84:87], v116 offset:14368
	s_waitcnt lgkmcnt(7)
	v_pk_fma_f32 v[128:129], v[88:89], v[36:37], v[128:129]
	v_pk_fma_f32 v[130:131], v[90:91], v[34:35], v[130:131]
	ds_read_b128 v[88:91], v116 offset:14384
	s_waitcnt lgkmcnt(7)
	v_pk_fma_f32 v[128:129], v[92:93], v[30:31], v[128:129]
	v_pk_fma_f32 v[130:131], v[94:95], v[26:27], v[130:131]
	ds_read_b128 v[92:95], v116 offset:14400
	s_waitcnt lgkmcnt(7)
	v_pk_fma_f32 v[128:129], v[96:97], v[24:25], v[128:129]
	v_pk_fma_f32 v[130:131], v[98:99], v[20:21], v[130:131]
	ds_read_b128 v[96:99], v116 offset:14416
	s_waitcnt lgkmcnt(7)
	v_pk_fma_f32 v[128:129], v[100:101], v[18:19], v[128:129]
	v_pk_fma_f32 v[130:131], v[102:103], v[14:15], v[130:131]
	ds_read_b128 v[100:103], v116 offset:14432
	s_waitcnt lgkmcnt(7)
	v_pk_fma_f32 v[128:129], v[104:105], v[10:11], v[128:129]
	v_pk_add_f32 v[124:125], v[124:125], v[126:127]
	v_add_f32_e32 v132, v124, v125
	v_sub_f32_e32 v8, v8, v132
	v_pk_fma_f32 v[130:131], v[106:107], v[8:9], v[130:131]
	ds_read_b128 v[104:107], v116 offset:14448
	s_waitcnt lgkmcnt(7)
	v_pk_mul_f32 v[124:125], v[108:109], v[4:5] op_sel:[0,1] op_sel_hi:[1,0]
	v_pk_mul_f32 v[126:127], v[110:111], v[70:71]
	ds_read_b128 v[108:111], v116 offset:14464
	s_waitcnt lgkmcnt(7)
	v_pk_fma_f32 v[124:125], v[112:113], v[74:75], v[124:125]
	v_pk_fma_f32 v[126:127], v[114:115], v[80:81], v[126:127]
	ds_read_b128 v[112:115], v116 offset:14480
	s_waitcnt lgkmcnt(7)
	v_pk_fma_f32 v[124:125], v[84:85], v[78:79], v[124:125]
	v_pk_fma_f32 v[126:127], v[86:87], v[76:77], v[126:127]
	ds_read_b128 v[84:87], v116 offset:14496
	s_waitcnt lgkmcnt(7)
	v_pk_fma_f32 v[124:125], v[88:89], v[72:73], v[124:125]
	v_pk_fma_f32 v[126:127], v[90:91], v[66:67], v[126:127]
	ds_read_b128 v[88:91], v116 offset:14512
	s_waitcnt lgkmcnt(7)
; __device__ __forceinline__ void gd_prep_item(CArgs* a, LAS unsigned char* lds, int l, int item) {
;     ...
;         for (int t = 1; t < 64; ++t) nrow[t] = NM[t * 64 + lane];
; #pragma unroll
;         for (int t = 1; t < 64; ++t) { float s0 = 0.f, s1 = 0.f;
; #pragma unroll
;             for (int sI = 0; sI < t; ++sI) { const float cf = __builtin_bit_cast(float, __builtin_amdgcn_readlane(__builtin_bit_cast(int, nrow[t]), sI)); if (sI & 1) s1 += cf * x[sI]; else s0 += cf * x[sI]; }
;             x[t] -= s0 + s1; }
	v_pk_fma_f32 v[124:125], v[92:93], v[64:65], v[124:125]
	v_pk_fma_f32 v[126:127], v[94:95], v[62:63], v[126:127]
	ds_read_b128 v[92:95], v116 offset:14528
	s_waitcnt lgkmcnt(7)
	v_pk_fma_f32 v[124:125], v[96:97], v[60:61], v[124:125]
	v_pk_fma_f32 v[126:127], v[98:99], v[56:57], v[126:127]
	ds_read_b128 v[96:99], v116 offset:14544
	s_waitcnt lgkmcnt(7)
	v_pk_fma_f32 v[124:125], v[100:101], v[54:55], v[124:125]
	v_pk_fma_f32 v[126:127], v[102:103], v[52:53], v[126:127]
	ds_read_b128 v[100:103], v116 offset:14592
	s_waitcnt lgkmcnt(7)
	v_pk_fma_f32 v[124:125], v[104:105], v[48:49], v[124:125]
	v_pk_fma_f32 v[126:127], v[106:107], v[46:47], v[126:127]
	ds_read_b128 v[104:107], v116 offset:14608
	s_waitcnt lgkmcnt(7)
	v_pk_fma_f32 v[124:125], v[108:109], v[42:43], v[124:125]
	v_pk_fma_f32 v[126:127], v[110:111], v[40:41], v[126:127]
	ds_read_b128 v[108:111], v116 offset:14624
	s_waitcnt lgkmcnt(7)
	v_pk_fma_f32 v[124:125], v[112:113], v[36:37], v[124:125]
	v_pk_fma_f32 v[126:127], v[114:115], v[34:35], v[126:127]
	ds_read_b128 v[112:115], v116 offset:14640
	s_waitcnt lgkmcnt(7)
	v_pk_fma_f32 v[124:125], v[84:85], v[30:31], v[124:125]
	v_pk_fma_f32 v[126:127], v[86:87], v[26:27], v[126:127]
	ds_read_b128 v[84:87], v116 offset:14656
	s_waitcnt lgkmcnt(7)
	v_pk_fma_f32 v[124:125], v[88:89], v[24:25], v[124:125]
	v_pk_fma_f32 v[126:127], v[90:91], v[20:21], v[126:127]
	ds_read_b128 v[88:91], v116 offset:14672
	s_waitcnt lgkmcnt(7)
	v_pk_fma_f32 v[124:125], v[92:93], v[18:19], v[124:125]
	v_pk_fma_f32 v[126:127], v[94:95], v[14:15], v[126:127]
	ds_read_b128 v[92:95], v116 offset:14688
	s_waitcnt lgkmcnt(7)
	v_pk_fma_f32 v[124:125], v[96:97], v[10:11], v[124:125]
	v_pk_add_f32 v[128:129], v[128:129], v[130:131]
	v_add_f32_e32 v133, v128, v129
	v_sub_f32_e32 v9, v9, v133
	v_pk_fma_f32 v[126:127], v[98:99], v[8:9], v[126:127]
	ds_read_b128 v[96:99], v116 offset:14704
	s_waitcnt lgkmcnt(7)
	v_pk_mul_f32 v[128:129], v[100:101], v[4:5] op_sel:[0,1] op_sel_hi:[1,0]
	v_pk_mul_f32 v[130:131], v[102:103], v[70:71]
	ds_read_b128 v[100:103], v116 offset:14720
	s_waitcnt lgkmcnt(7)
	v_pk_fma_f32 v[128:129], v[104:105], v[74:75], v[128:129]
	v_pk_fma_f32 v[130:131], v[106:107], v[80:81], v[130:131]
	ds_read_b128 v[104:107], v116 offset:14736
	s_waitcnt lgkmcnt(7)
	v_pk_fma_f32 v[128:129], v[108:109], v[78:79], v[128:129]
	v_pk_fma_f32 v[130:131], v[110:111], v[76:77], v[130:131]
	ds_read_b128 v[108:111], v116 offset:14752
	s_waitcnt lgkmcnt(7)
	v_pk_fma_f32 v[128:129], v[112:113], v[72:73], v[128:129]
	v_pk_fma_f32 v[130:131], v[114:115], v[66:67], v[130:131]
	ds_read_b128 v[112:115], v116 offset:14768
	s_waitcnt lgkmcnt(7)
	v_pk_fma_f32 v[128:129], v[84:85], v[64:65], v[128:129]
	v_pk_fma_f32 v[130:131], v[86:87], v[62:63], v[130:131]
	ds_read_b128 v[84:87], v116 offset:14784
	s_waitcnt lgkmcnt(7)
	v_pk_fma_f32 v[128:129], v[88:89], v[60:61], v[128:129]
	v_pk_fma_f32 v[130:131], v[90:91], v[56:57], v[130:131]
	ds_read_b128 v[88:91], v116 offset:14800
	s_waitcnt lgkmcnt(7)
	v_pk_fma_f32 v[128:129], v[92:93], v[54:55], v[128:129]
	v_pk_fma_f32 v[130:131], v[94:95], v[52:53], v[130:131]
	ds_read_b128 v[92:95], v116 offset:14816
	s_waitcnt lgkmcnt(7)
	v_pk_fma_f32 v[128:129], v[96:97], v[48:49], v[128:129]
	v_pk_fma_f32 v[130:131], v[98:99], v[46:47], v[130:131]
	ds_read_b128 v[96:99], v116 offset:14848
	s_waitcnt lgkmcnt(7)
	v_pk_fma_f32 v[128:129], v[100:101], v[42:43], v[128:129]
	v_pk_fma_f32 v[130:131], v[102:103], v[40:41], v[130:131]
	ds_read_b128 v[100:103], v116 offset:14864
	s_waitcnt lgkmcnt(7)
	v_pk_fma_f32 v[128:129], v[104:105], v[36:37], v[128:129]
	v_pk_fma_f32 v[130:131], v[106:107], v[34:35], v[130:131]
	ds_read_b128 v[104:107], v116 offset:14880
	s_waitcnt lgkmcnt(7)
	v_pk_fma_f32 v[128:129], v[108:109], v[30:31], v[128:129]
	v_pk_fma_f32 v[130:131], v[110:111], v[26:27], v[130:131]
	ds_read_b128 v[108:111], v116 offset:14896
	s_waitcnt lgkmcnt(7)
	v_pk_fma_f32 v[128:129], v[112:113], v[24:25], v[128:129]
	v_pk_fma_f32 v[130:131], v[114:115], v[20:21], v[130:131]
	ds_read_b128 v[112:115], v116 offset:14912
	s_waitcnt lgkmcnt(7)
	v_pk_fma_f32 v[128:129], v[84:85], v[18:19], v[128:129]
	v_pk_fma_f32 v[130:131], v[86:87], v[14:15], v[130:131]
	ds_read_b128 v[84:87], v116 offset:14928
	s_waitcnt lgkmcnt(7)
	v_pk_fma_f32 v[128:129], v[88:89], v[10:11], v[128:129]
	v_pk_fma_f32 v[130:131], v[90:91], v[8:9], v[130:131]
	ds_read_b128 v[88:91], v116 offset:14944
	v_pk_add_f32 v[124:125], v[124:125], v[126:127]
	v_add_f32_e32 v132, v124, v125
	v_sub_f32_e32 v6, v6, v132
	s_waitcnt lgkmcnt(7)
	v_pk_fma_f32 v[128:129], v[92:93], v[6:7], v[128:129]
	ds_read_b128 v[92:95], v116 offset:14960
	s_waitcnt lgkmcnt(7)
	v_pk_mul_f32 v[124:125], v[96:97], v[4:5] op_sel:[0,1] op_sel_hi:[1,0]
	v_pk_mul_f32 v[126:127], v[98:99], v[70:71]
	ds_read_b128 v[96:99], v116 offset:14976
	s_waitcnt lgkmcnt(7)
	v_pk_fma_f32 v[124:125], v[100:101], v[74:75], v[124:125]
	v_pk_fma_f32 v[126:127], v[102:103], v[80:81], v[126:127]
	ds_read_b128 v[100:103], v116 offset:14992
	s_waitcnt lgkmcnt(7)
	v_pk_fma_f32 v[124:125], v[104:105], v[78:79], v[124:125]
	v_pk_fma_f32 v[126:127], v[106:107], v[76:77], v[126:127]
	ds_read_b128 v[104:107], v116 offset:15008
	s_waitcnt lgkmcnt(7)
	v_pk_fma_f32 v[124:125], v[108:109], v[72:73], v[124:125]
	v_pk_fma_f32 v[126:127], v[110:111], v[66:67], v[126:127]
	ds_read_b128 v[108:111], v116 offset:15024
	s_waitcnt lgkmcnt(7)
	v_pk_fma_f32 v[124:125], v[112:113], v[64:65], v[124:125]
	v_pk_fma_f32 v[126:127], v[114:115], v[62:63], v[126:127]
	ds_read_b128 v[112:115], v116 offset:15040
	s_waitcnt lgkmcnt(7)
; __device__ __forceinline__ void gd_prep_item(CArgs* a, LAS unsigned char* lds, int l, int item) {
;     ...
;         for (int t = 1; t < 64; ++t) nrow[t] = NM[t * 64 + lane];
; #pragma unroll
;         for (int t = 1; t < 64; ++t) { float s0 = 0.f, s1 = 0.f;
; #pragma unroll
;             for (int sI = 0; sI < t; ++sI) { const float cf = __builtin_bit_cast(float, __builtin_amdgcn_readlane(__builtin_bit_cast(int, nrow[t]), sI)); if (sI & 1) s1 += cf * x[sI]; else s0 += cf * x[sI]; }
;             x[t] -= s0 + s1; }
	v_pk_fma_f32 v[124:125], v[84:85], v[60:61], v[124:125]
	v_pk_fma_f32 v[126:127], v[86:87], v[56:57], v[126:127]
	ds_read_b128 v[84:87], v116 offset:15056
	s_waitcnt lgkmcnt(7)
	v_pk_fma_f32 v[124:125], v[88:89], v[54:55], v[124:125]
	v_pk_fma_f32 v[126:127], v[90:91], v[52:53], v[126:127]
	ds_read_b128 v[88:91], v116 offset:15072
	s_waitcnt lgkmcnt(7)
	v_pk_fma_f32 v[124:125], v[92:93], v[48:49], v[124:125]
	v_pk_fma_f32 v[126:127], v[94:95], v[46:47], v[126:127]
	ds_read_b128 v[92:95], v116 offset:15104
	s_waitcnt lgkmcnt(7)
	v_pk_fma_f32 v[124:125], v[96:97], v[42:43], v[124:125]
	v_pk_fma_f32 v[126:127], v[98:99], v[40:41], v[126:127]
	ds_read_b128 v[96:99], v116 offset:15120
	s_waitcnt lgkmcnt(7)
	v_pk_fma_f32 v[124:125], v[100:101], v[36:37], v[124:125]
	v_pk_fma_f32 v[126:127], v[102:103], v[34:35], v[126:127]
	ds_read_b128 v[100:103], v116 offset:15136
	s_waitcnt lgkmcnt(7)
	v_pk_fma_f32 v[124:125], v[104:105], v[30:31], v[124:125]
	v_pk_fma_f32 v[126:127], v[106:107], v[26:27], v[126:127]
	ds_read_b128 v[104:107], v116 offset:15152
	s_waitcnt lgkmcnt(7)
	v_pk_fma_f32 v[124:125], v[108:109], v[24:25], v[124:125]
	v_pk_fma_f32 v[126:127], v[110:111], v[20:21], v[126:127]
	ds_read_b128 v[108:111], v116 offset:15168
	s_waitcnt lgkmcnt(7)
	v_pk_fma_f32 v[124:125], v[112:113], v[18:19], v[124:125]
	v_pk_fma_f32 v[126:127], v[114:115], v[14:15], v[126:127]
	ds_read_b128 v[112:115], v116 offset:15184
	s_waitcnt lgkmcnt(7)
	v_pk_fma_f32 v[124:125], v[84:85], v[10:11], v[124:125]
	v_pk_fma_f32 v[126:127], v[86:87], v[8:9], v[126:127]
	ds_read_b128 v[84:87], v116 offset:15200
	v_pk_add_f32 v[128:129], v[128:129], v[130:131]
	v_add_f32_e32 v133, v128, v129
	v_sub_f32_e32 v7, v7, v133
	s_waitcnt lgkmcnt(7)
	v_pk_fma_f32 v[124:125], v[88:89], v[6:7], v[124:125]
	ds_read_b128 v[88:91], v116 offset:15216
	s_waitcnt lgkmcnt(7)
	v_pk_mul_f32 v[128:129], v[92:93], v[4:5] op_sel:[0,1] op_sel_hi:[1,0]
	v_pk_mul_f32 v[130:131], v[94:95], v[70:71]
	ds_read_b128 v[92:95], v116 offset:15232
	s_waitcnt lgkmcnt(7)
	v_pk_fma_f32 v[128:129], v[96:97], v[74:75], v[128:129]
	v_pk_fma_f32 v[130:131], v[98:99], v[80:81], v[130:131]
	ds_read_b128 v[96:99], v116 offset:15248
	s_waitcnt lgkmcnt(7)
	v_pk_fma_f32 v[128:129], v[100:101], v[78:79], v[128:129]
	v_pk_fma_f32 v[130:131], v[102:103], v[76:77], v[130:131]
	ds_read_b128 v[100:103], v116 offset:15264
	s_waitcnt lgkmcnt(7)
	v_pk_fma_f32 v[128:129], v[104:105], v[72:73], v[128:129]
	v_pk_fma_f32 v[130:131], v[106:107], v[66:67], v[130:131]
	ds_read_b128 v[104:107], v116 offset:15280
	s_waitcnt lgkmcnt(7)
	v_pk_fma_f32 v[128:129], v[108:109], v[64:65], v[128:129]
	v_pk_fma_f32 v[130:131], v[110:111], v[62:63], v[130:131]
	ds_read_b128 v[108:111], v116 offset:15296
	s_waitcnt lgkmcnt(7)
	v_pk_fma_f32 v[128:129], v[112:113], v[60:61], v[128:129]
	v_pk_fma_f32 v[130:131], v[114:115], v[56:57], v[130:131]
	ds_read_b128 v[112:115], v116 offset:15312
	s_waitcnt lgkmcnt(7)
	v_pk_fma_f32 v[128:129], v[84:85], v[54:55], v[128:129]
	v_pk_fma_f32 v[130:131], v[86:87], v[52:53], v[130:131]
	ds_read_b128 v[84:87], v116 offset:15328
	s_waitcnt lgkmcnt(7)
	v_pk_fma_f32 v[128:129], v[88:89], v[48:49], v[128:129]
	v_pk_fma_f32 v[130:131], v[90:91], v[46:47], v[130:131]
	ds_read_b128 v[88:91], v116 offset:15360
	s_waitcnt lgkmcnt(7)
	v_pk_fma_f32 v[128:129], v[92:93], v[42:43], v[128:129]
	v_pk_fma_f32 v[130:131], v[94:95], v[40:41], v[130:131]
	ds_read_b128 v[92:95], v116 offset:15376
	s_waitcnt lgkmcnt(7)
	v_pk_fma_f32 v[128:129], v[96:97], v[36:37], v[128:129]
	v_pk_fma_f32 v[130:131], v[98:99], v[34:35], v[130:131]
	ds_read_b128 v[96:99], v116 offset:15392
	s_waitcnt lgkmcnt(7)
	v_pk_fma_f32 v[128:129], v[100:101], v[30:31], v[128:129]
	v_pk_fma_f32 v[130:131], v[102:103], v[26:27], v[130:131]
	ds_read_b128 v[100:103], v116 offset:15408
	s_waitcnt lgkmcnt(7)
	v_pk_fma_f32 v[128:129], v[104:105], v[24:25], v[128:129]
	v_pk_fma_f32 v[130:131], v[106:107], v[20:21], v[130:131]
	ds_read_b128 v[104:107], v116 offset:15424
	s_waitcnt lgkmcnt(7)
	v_pk_fma_f32 v[128:129], v[108:109], v[18:19], v[128:129]
	v_pk_fma_f32 v[130:131], v[110:111], v[14:15], v[130:131]
	ds_read_b128 v[108:111], v116 offset:15440
	s_waitcnt lgkmcnt(7)
	v_pk_fma_f32 v[128:129], v[112:113], v[10:11], v[128:129]
	v_pk_fma_f32 v[130:131], v[114:115], v[8:9], v[130:131]
	ds_read_b128 v[112:115], v116 offset:15456
	s_waitcnt lgkmcnt(7)
	v_pk_fma_f32 v[128:129], v[84:85], v[6:7], v[128:129]
	v_pk_add_f32 v[124:125], v[124:125], v[126:127]
	v_add_f32_e32 v132, v124, v125
	v_sub_f32_e32 v16, v16, v132
	v_pk_fma_f32 v[130:131], v[86:87], v[16:17], v[130:131]
	ds_read_b128 v[84:87], v116 offset:15472
	s_waitcnt lgkmcnt(7)
	v_pk_mul_f32 v[124:125], v[88:89], v[4:5] op_sel:[0,1] op_sel_hi:[1,0]
	v_pk_mul_f32 v[126:127], v[90:91], v[70:71]
	ds_read_b128 v[88:91], v116 offset:15488
	s_waitcnt lgkmcnt(7)
	v_pk_fma_f32 v[124:125], v[92:93], v[74:75], v[124:125]
	v_pk_fma_f32 v[126:127], v[94:95], v[80:81], v[126:127]
	ds_read_b128 v[92:95], v116 offset:15504
	s_waitcnt lgkmcnt(7)
	v_pk_fma_f32 v[124:125], v[96:97], v[78:79], v[124:125]
	v_pk_fma_f32 v[126:127], v[98:99], v[76:77], v[126:127]
	ds_read_b128 v[96:99], v116 offset:15520
	s_waitcnt lgkmcnt(7)
	v_pk_fma_f32 v[124:125], v[100:101], v[72:73], v[124:125]
	v_pk_fma_f32 v[126:127], v[102:103], v[66:67], v[126:127]
	ds_read_b128 v[100:103], v116 offset:15536
	s_waitcnt lgkmcnt(7)
	v_pk_fma_f32 v[124:125], v[104:105], v[64:65], v[124:125]
	v_pk_fma_f32 v[126:127], v[106:107], v[62:63], v[126:127]
	ds_read_b128 v[104:107], v116 offset:15552
	s_waitcnt lgkmcnt(7)
; __device__ __forceinline__ void gd_prep_item(CArgs* a, LAS unsigned char* lds, int l, int item) {
;     ...
;         for (int t = 1; t < 64; ++t) nrow[t] = NM[t * 64 + lane];
; #pragma unroll
;         for (int t = 1; t < 64; ++t) { float s0 = 0.f, s1 = 0.f;
; #pragma unroll
;             for (int sI = 0; sI < t; ++sI) { const float cf = __builtin_bit_cast(float, __builtin_amdgcn_readlane(__builtin_bit_cast(int, nrow[t]), sI)); if (sI & 1) s1 += cf * x[sI]; else s0 += cf * x[sI]; }
;             x[t] -= s0 + s1; }
	v_pk_fma_f32 v[124:125], v[108:109], v[60:61], v[124:125]
	v_pk_fma_f32 v[126:127], v[110:111], v[56:57], v[126:127]
	ds_read_b128 v[108:111], v116 offset:15568
	s_waitcnt lgkmcnt(7)
	v_pk_fma_f32 v[124:125], v[112:113], v[54:55], v[124:125]
	v_pk_fma_f32 v[126:127], v[114:115], v[52:53], v[126:127]
	ds_read_b128 v[112:115], v116 offset:15584
	s_waitcnt lgkmcnt(7)
	v_pk_fma_f32 v[124:125], v[84:85], v[48:49], v[124:125]
	v_pk_fma_f32 v[126:127], v[86:87], v[46:47], v[126:127]
	ds_read_b128 v[84:87], v116 offset:15616
	s_waitcnt lgkmcnt(7)
	v_pk_fma_f32 v[124:125], v[88:89], v[42:43], v[124:125]
	v_pk_fma_f32 v[126:127], v[90:91], v[40:41], v[126:127]
	ds_read_b128 v[88:91], v116 offset:15632
	s_waitcnt lgkmcnt(7)
	v_pk_fma_f32 v[124:125], v[92:93], v[36:37], v[124:125]
	v_pk_fma_f32 v[126:127], v[94:95], v[34:35], v[126:127]
	ds_read_b128 v[92:95], v116 offset:15648
	s_waitcnt lgkmcnt(7)
	v_pk_fma_f32 v[124:125], v[96:97], v[30:31], v[124:125]
	v_pk_fma_f32 v[126:127], v[98:99], v[26:27], v[126:127]
	ds_read_b128 v[96:99], v116 offset:15664
	s_waitcnt lgkmcnt(7)
	v_pk_fma_f32 v[124:125], v[100:101], v[24:25], v[124:125]
	v_pk_fma_f32 v[126:127], v[102:103], v[20:21], v[126:127]
	ds_read_b128 v[100:103], v116 offset:15680
	s_waitcnt lgkmcnt(7)
	v_pk_fma_f32 v[124:125], v[104:105], v[18:19], v[124:125]
	v_pk_fma_f32 v[126:127], v[106:107], v[14:15], v[126:127]
	ds_read_b128 v[104:107], v116 offset:15696
	s_waitcnt lgkmcnt(7)
	v_pk_fma_f32 v[124:125], v[108:109], v[10:11], v[124:125]
	v_pk_fma_f32 v[126:127], v[110:111], v[8:9], v[126:127]
	ds_read_b128 v[108:111], v116 offset:15712
	s_waitcnt lgkmcnt(7)
	v_pk_fma_f32 v[124:125], v[112:113], v[6:7], v[124:125]
	v_pk_add_f32 v[128:129], v[128:129], v[130:131]
	v_add_f32_e32 v133, v128, v129
	v_sub_f32_e32 v17, v17, v133
	v_pk_fma_f32 v[126:127], v[114:115], v[16:17], v[126:127]
	ds_read_b128 v[112:115], v116 offset:15728
	s_waitcnt lgkmcnt(7)
	v_pk_mul_f32 v[128:129], v[84:85], v[4:5] op_sel:[0,1] op_sel_hi:[1,0]
	v_pk_mul_f32 v[130:131], v[86:87], v[70:71]
	ds_read_b128 v[84:87], v116 offset:15744
	s_waitcnt lgkmcnt(7)
	v_pk_fma_f32 v[128:129], v[88:89], v[74:75], v[128:129]
	v_pk_fma_f32 v[130:131], v[90:91], v[80:81], v[130:131]
	ds_read_b128 v[88:91], v116 offset:15760
	s_waitcnt lgkmcnt(7)
	v_pk_fma_f32 v[128:129], v[92:93], v[78:79], v[128:129]
	v_pk_fma_f32 v[130:131], v[94:95], v[76:77], v[130:131]
	ds_read_b128 v[92:95], v116 offset:15776
	s_waitcnt lgkmcnt(7)
	v_pk_fma_f32 v[128:129], v[96:97], v[72:73], v[128:129]
	v_pk_fma_f32 v[130:131], v[98:99], v[66:67], v[130:131]
	ds_read_b128 v[96:99], v116 offset:15792
	s_waitcnt lgkmcnt(7)
	v_pk_fma_f32 v[128:129], v[100:101], v[64:65], v[128:129]
	v_pk_fma_f32 v[130:131], v[102:103], v[62:63], v[130:131]
	ds_read_b128 v[100:103], v116 offset:15808
	s_waitcnt lgkmcnt(7)
	v_pk_fma_f32 v[128:129], v[104:105], v[60:61], v[128:129]
	v_pk_fma_f32 v[130:131], v[106:107], v[56:57], v[130:131]
	ds_read_b128 v[104:107], v116 offset:15824
	s_waitcnt lgkmcnt(7)
	v_pk_fma_f32 v[128:129], v[108:109], v[54:55], v[128:129]
	v_pk_fma_f32 v[130:131], v[110:111], v[52:53], v[130:131]
	ds_read_b128 v[108:111], v116 offset:15840
	s_waitcnt lgkmcnt(7)
	v_pk_fma_f32 v[128:129], v[112:113], v[48:49], v[128:129]
	v_pk_fma_f32 v[130:131], v[114:115], v[46:47], v[130:131]
	ds_read_b128 v[112:115], v116 offset:15856
	s_waitcnt lgkmcnt(7)
	v_pk_fma_f32 v[128:129], v[84:85], v[42:43], v[128:129]
	v_pk_fma_f32 v[130:131], v[86:87], v[40:41], v[130:131]
	ds_read_b128 v[84:87], v116 offset:15872
	s_waitcnt lgkmcnt(7)
	v_pk_fma_f32 v[128:129], v[88:89], v[36:37], v[128:129]
	v_pk_fma_f32 v[130:131], v[90:91], v[34:35], v[130:131]
	ds_read_b128 v[88:91], v116 offset:15888
	s_waitcnt lgkmcnt(7)
	v_pk_fma_f32 v[128:129], v[92:93], v[30:31], v[128:129]
	v_pk_fma_f32 v[130:131], v[94:95], v[26:27], v[130:131]
	ds_read_b128 v[92:95], v116 offset:15904
	s_waitcnt lgkmcnt(7)
	v_pk_fma_f32 v[128:129], v[96:97], v[24:25], v[128:129]
	v_pk_fma_f32 v[130:131], v[98:99], v[20:21], v[130:131]
	ds_read_b128 v[96:99], v116 offset:15920
	s_waitcnt lgkmcnt(7)
	v_pk_fma_f32 v[128:129], v[100:101], v[18:19], v[128:129]
	v_pk_fma_f32 v[130:131], v[102:103], v[14:15], v[130:131]
	ds_read_b128 v[100:103], v116 offset:15936
	s_waitcnt lgkmcnt(7)
	v_pk_fma_f32 v[128:129], v[104:105], v[10:11], v[128:129]
	v_pk_fma_f32 v[130:131], v[106:107], v[8:9], v[130:131]
	ds_read_b128 v[104:107], v116 offset:15952
	s_waitcnt lgkmcnt(7)
	v_pk_fma_f32 v[128:129], v[108:109], v[6:7], v[128:129]
	v_pk_fma_f32 v[130:131], v[110:111], v[16:17], v[130:131]
	ds_read_b128 v[108:111], v116 offset:15968
	v_pk_add_f32 v[124:125], v[124:125], v[126:127]
	v_add_f32_e32 v132, v124, v125
	v_sub_f32_e32 v12, v12, v132
	s_waitcnt lgkmcnt(7)
	v_pk_fma_f32 v[128:129], v[112:113], v[12:13], v[128:129]
	ds_read_b128 v[112:115], v116 offset:15984
	s_waitcnt lgkmcnt(7)
	v_pk_mul_f32 v[124:125], v[84:85], v[4:5] op_sel:[0,1] op_sel_hi:[1,0]
	v_pk_mul_f32 v[126:127], v[86:87], v[70:71]
	ds_read_b128 v[84:87], v116 offset:16000
	s_waitcnt lgkmcnt(7)
	v_pk_fma_f32 v[124:125], v[88:89], v[74:75], v[124:125]
	v_pk_fma_f32 v[126:127], v[90:91], v[80:81], v[126:127]
	ds_read_b128 v[88:91], v116 offset:16016
	s_waitcnt lgkmcnt(7)
	v_pk_fma_f32 v[124:125], v[92:93], v[78:79], v[124:125]
	v_pk_fma_f32 v[126:127], v[94:95], v[76:77], v[126:127]
	ds_read_b128 v[92:95], v116 offset:16032
	s_waitcnt lgkmcnt(7)
	v_pk_fma_f32 v[124:125], v[96:97], v[72:73], v[124:125]
	v_pk_fma_f32 v[126:127], v[98:99], v[66:67], v[126:127]
	ds_read_b128 v[96:99], v116 offset:16048
	s_waitcnt lgkmcnt(7)
; __device__ __forceinline__ void gd_prep_item(CArgs* a, LAS unsigned char* lds, int l, int item) {
;     ...
;         for (int t = 1; t < 64; ++t) { float s0 = 0.f, s1 = 0.f;
; #pragma unroll
;             for (int sI = 0; sI < t; ++sI) { const float cf = __builtin_bit_cast(float, __builtin_amdgcn_readlane(__builtin_bit_cast(int, nrow[t]), sI)); if (sI & 1) s1 += cf * x[sI]; else s0 += cf * x[sI]; }
;             x[t] -= s0 + s1; }
;         if (col < 128) { const int vb = col >> 4, r = col & 15;
	v_pk_fma_f32 v[124:125], v[100:101], v[64:65], v[124:125]
	v_pk_fma_f32 v[126:127], v[102:103], v[62:63], v[126:127]
	ds_read_b128 v[100:103], v116 offset:16064
	s_waitcnt lgkmcnt(7)
	v_pk_fma_f32 v[124:125], v[104:105], v[60:61], v[124:125]
	v_pk_fma_f32 v[126:127], v[106:107], v[56:57], v[126:127]
	ds_read_b128 v[104:107], v116 offset:16080
	s_waitcnt lgkmcnt(7)
	v_pk_fma_f32 v[124:125], v[108:109], v[54:55], v[124:125]
	v_pk_fma_f32 v[126:127], v[110:111], v[52:53], v[126:127]
	ds_read_b128 v[108:111], v116 offset:16096
	s_waitcnt lgkmcnt(7)
	v_pk_fma_f32 v[124:125], v[112:113], v[48:49], v[124:125]
	v_pk_fma_f32 v[126:127], v[114:115], v[46:47], v[126:127]
	ds_read_b128 v[112:115], v116 offset:16112
	s_waitcnt lgkmcnt(7)
	v_pk_fma_f32 v[124:125], v[84:85], v[42:43], v[124:125]
	v_pk_fma_f32 v[126:127], v[86:87], v[40:41], v[126:127]
	ds_read_b128 v[84:87], v116 offset:16128
	s_waitcnt lgkmcnt(7)
	v_pk_fma_f32 v[124:125], v[88:89], v[36:37], v[124:125]
	v_pk_fma_f32 v[126:127], v[90:91], v[34:35], v[126:127]
	ds_read_b128 v[88:91], v116 offset:16144
	s_waitcnt lgkmcnt(7)
	v_pk_fma_f32 v[124:125], v[92:93], v[30:31], v[124:125]
	v_pk_fma_f32 v[126:127], v[94:95], v[26:27], v[126:127]
	ds_read_b128 v[92:95], v116 offset:16160
	s_waitcnt lgkmcnt(7)
	v_pk_fma_f32 v[124:125], v[96:97], v[24:25], v[124:125]
	v_pk_fma_f32 v[126:127], v[98:99], v[20:21], v[126:127]
	ds_read_b128 v[96:99], v116 offset:16176
	s_waitcnt lgkmcnt(7)
	v_pk_fma_f32 v[124:125], v[100:101], v[18:19], v[124:125]
	v_pk_fma_f32 v[126:127], v[102:103], v[14:15], v[126:127]
	ds_read_b128 v[100:103], v116 offset:16192
	s_waitcnt lgkmcnt(7)
	v_pk_fma_f32 v[124:125], v[104:105], v[10:11], v[124:125]
	v_pk_fma_f32 v[126:127], v[106:107], v[8:9], v[126:127]
	ds_read_b128 v[104:107], v116 offset:16208
	s_waitcnt lgkmcnt(7)
	v_pk_fma_f32 v[124:125], v[108:109], v[6:7], v[124:125]
	v_pk_fma_f32 v[126:127], v[110:111], v[16:17], v[126:127]
	ds_read_b128 v[108:111], v116 offset:16224
	v_pk_add_f32 v[128:129], v[128:129], v[130:131]
	v_add_f32_e32 v133, v128, v129
	v_sub_f32_e32 v13, v13, v133
	s_waitcnt lgkmcnt(7)
	v_pk_fma_f32 v[124:125], v[112:113], v[12:13], v[124:125]
	ds_read_b128 v[112:115], v116 offset:16240
	s_waitcnt lgkmcnt(7)
	v_pk_mul_f32 v[128:129], v[84:85], v[4:5] op_sel:[0,1] op_sel_hi:[1,0]
	v_pk_mul_f32 v[130:131], v[86:87], v[70:71]
	ds_read_b128 v[84:87], v116 offset:16256
	s_waitcnt lgkmcnt(7)
	v_pk_fma_f32 v[128:129], v[88:89], v[74:75], v[128:129]
	v_pk_fma_f32 v[130:131], v[90:91], v[80:81], v[130:131]
	ds_read_b128 v[88:91], v116 offset:16272
	s_waitcnt lgkmcnt(7)
	v_pk_fma_f32 v[128:129], v[92:93], v[78:79], v[128:129]
	v_pk_fma_f32 v[130:131], v[94:95], v[76:77], v[130:131]
	ds_read_b128 v[92:95], v116 offset:16288
	s_waitcnt lgkmcnt(7)
	v_pk_fma_f32 v[128:129], v[96:97], v[72:73], v[128:129]
	v_pk_fma_f32 v[130:131], v[98:99], v[66:67], v[130:131]
	ds_read_b128 v[96:99], v116 offset:16304
	s_waitcnt lgkmcnt(7)
	v_pk_fma_f32 v[128:129], v[100:101], v[64:65], v[128:129]
	v_pk_fma_f32 v[130:131], v[102:103], v[62:63], v[130:131]
	ds_read_b128 v[100:103], v116 offset:16320
	s_waitcnt lgkmcnt(7)
	v_pk_fma_f32 v[128:129], v[104:105], v[60:61], v[128:129]
	v_pk_fma_f32 v[130:131], v[106:107], v[56:57], v[130:131]
	ds_read_b128 v[104:107], v116 offset:16336
	s_waitcnt lgkmcnt(7)
	v_pk_fma_f32 v[128:129], v[108:109], v[54:55], v[128:129]
	v_pk_fma_f32 v[130:131], v[110:111], v[52:53], v[130:131]
	ds_read_b128 v[108:111], v116 offset:16352
	s_waitcnt lgkmcnt(7)
	v_pk_fma_f32 v[128:129], v[112:113], v[48:49], v[128:129]
	v_pk_fma_f32 v[130:131], v[114:115], v[46:47], v[130:131]
	ds_read_b128 v[112:115], v116 offset:16368
	s_waitcnt lgkmcnt(7)
	v_pk_fma_f32 v[128:129], v[84:85], v[42:43], v[128:129]
	v_pk_fma_f32 v[130:131], v[86:87], v[40:41], v[130:131]
	s_waitcnt lgkmcnt(6)
	v_pk_fma_f32 v[128:129], v[88:89], v[36:37], v[128:129]
	v_pk_fma_f32 v[130:131], v[90:91], v[34:35], v[130:131]
	s_waitcnt lgkmcnt(5)
	v_pk_fma_f32 v[128:129], v[92:93], v[30:31], v[128:129]
	v_pk_fma_f32 v[130:131], v[94:95], v[26:27], v[130:131]
	s_waitcnt lgkmcnt(4)
	v_pk_fma_f32 v[128:129], v[96:97], v[24:25], v[128:129]
	v_pk_fma_f32 v[130:131], v[98:99], v[20:21], v[130:131]
	s_waitcnt lgkmcnt(3)
	v_pk_fma_f32 v[128:129], v[100:101], v[18:19], v[128:129]
	v_pk_fma_f32 v[130:131], v[102:103], v[14:15], v[130:131]
	s_waitcnt lgkmcnt(2)
	v_pk_fma_f32 v[128:129], v[104:105], v[10:11], v[128:129]
	v_pk_fma_f32 v[130:131], v[106:107], v[8:9], v[130:131]
	s_waitcnt lgkmcnt(1)
	v_pk_fma_f32 v[128:129], v[108:109], v[6:7], v[128:129]
	v_pk_fma_f32 v[130:131], v[110:111], v[16:17], v[130:131]
	s_waitcnt lgkmcnt(0)
	v_pk_fma_f32 v[128:129], v[112:113], v[12:13], v[128:129]
	v_pk_add_f32 v[124:125], v[124:125], v[126:127]
	v_add_f32_e32 v132, v124, v125
	v_sub_f32_e32 v22, v22, v132
	v_pk_fma_f32 v[130:131], v[114:115], v[22:23], v[130:131]
	v_pk_add_f32 v[128:129], v[128:129], v[130:131]
	v_add_f32_e32 v133, v128, v129
	v_sub_f32_e32 v23, v23, v133
	v_mov_b32_e32 v124, v70
	v_mov_b32_e32 v70, v74
	v_mov_b32_e32 v74, v75
	v_mov_b32_e32 v75, v80
	v_mov_b32_e32 v80, v81
	s_and_saveexec_b64 s[10:11], vcc
	s_xor_b64 s[10:11], exec, s[10:11]
	s_cbranch_execz .LBB0_991
; __device__ __forceinline__ bf16_t f2bf(float f) { return (bf16_t)(cvt_pk_bf16(f, 0.f) & 0xffffu); }
; __device__ __forceinline__ void gd_prep_item(CArgs* a, LAS unsigned char* lds, int l, int item) {
;     ...
;         else { const int d = col - 128, ks = d >> 5, dl = d & 31, q = (dl >> 2) & 3, j = (dl & 3) + 4 * (dl >> 4);
; #pragma unroll
;             for (int t = 0; t < 64; ++t) *(bf16_t*)(ops + OG_WN + (((t >> 4) * 4 + ks) * 64 + q * 16 + (t & 15)) * 16 + j * 2) = f2bf(-x[t]); }
	v_lshrrev_b32_e32 v28, 2, v3
	v_and_or_b32 v28, v28, 4, v122
	v_lshlrev_b32_e32 v3, 2, v3
	v_lshlrev_b32_e32 v28, 1, v28
	v_mov_b32_e32 v29, v2
	v_and_b32_e32 v3, 48, v3
	v_lshl_add_u64 v[28:29], s[8:9], 0, v[28:29]
	s_mov_b32 s8, 0xfffffc0
	v_and_or_b32 v3, v123, s8, v3
	v_lshlrev_b32_e32 v32, 4, v3
	v_add_u32_e32 v38, 0xfffff000, v32
	v_mov_b32_e32 v39, v2
	v_lshl_add_u64 v[38:39], v[28:29], 0, v[38:39]
	v_cvt_pk_bf16_f32 v3, -v4, s0
	global_store_short v[38:39], v3, off offset:16
	v_cvt_pk_bf16_f32 v3, -v124, s0
	global_store_short v[38:39], v3, off offset:32
	v_cvt_pk_bf16_f32 v3, -v71, s0
	global_store_short v[38:39], v3, off offset:48
	v_cvt_pk_bf16_f32 v3, -v70, s0
	global_store_short v[38:39], v3, off offset:64
	v_cvt_pk_bf16_f32 v3, -v74, s0
	global_store_short v[38:39], v3, off offset:80
	v_cvt_pk_bf16_f32 v3, -v75, s0
	global_store_short v[38:39], v3, off offset:96
	v_cvt_pk_bf16_f32 v3, -v80, s0
	global_store_short v[38:39], v3, off offset:112
	v_cvt_pk_bf16_f32 v3, -v78, s0
	global_store_short v[38:39], v3, off offset:128
	v_cvt_pk_bf16_f32 v3, -v79, s0
	global_store_short v[38:39], v3, off offset:144
	v_cvt_pk_bf16_f32 v3, -v76, s0
	global_store_short v[38:39], v3, off offset:160
	v_cvt_pk_bf16_f32 v3, -v77, s0
	global_store_short v[38:39], v3, off offset:176
	v_cvt_pk_bf16_f32 v3, -v72, s0
	global_store_short v[38:39], v3, off offset:192
	v_cvt_pk_bf16_f32 v3, -v73, s0
	global_store_short v[38:39], v3, off offset:208
	v_cvt_pk_bf16_f32 v3, -v66, s0
	v_cvt_pk_bf16_f32 v5, -v5, s0
	global_store_short v[38:39], v3, off offset:224
	v_cvt_pk_bf16_f32 v3, -v67, s0
	v_mov_b32_e32 v33, v2
	global_store_short v[38:39], v5, off
	global_store_short v[38:39], v3, off offset:240
	v_cvt_pk_bf16_f32 v3, -v64, s0
	v_lshl_add_u64 v[4:5], v[28:29], 0, v[32:33]
	v_ashrrev_i32_e32 v33, 31, v32
	global_store_short v[4:5], v3, off
	v_cvt_pk_bf16_f32 v3, -v65, s0
	v_lshl_add_u64 v[4:5], v[28:29], 0, v[32:33]
	global_store_short v[4:5], v3, off offset:16
	v_cvt_pk_bf16_f32 v3, -v62, s0
	global_store_short v[4:5], v3, off offset:32
	v_cvt_pk_bf16_f32 v3, -v63, s0
	global_store_short v[4:5], v3, off offset:48
	v_cvt_pk_bf16_f32 v3, -v60, s0
	global_store_short v[4:5], v3, off offset:64
	v_cvt_pk_bf16_f32 v3, -v61, s0
	global_store_short v[4:5], v3, off offset:80
	v_cvt_pk_bf16_f32 v3, -v56, s0
	global_store_short v[4:5], v3, off offset:96
	v_cvt_pk_bf16_f32 v3, -v57, s0
	global_store_short v[4:5], v3, off offset:112
	v_cvt_pk_bf16_f32 v3, -v54, s0
	global_store_short v[4:5], v3, off offset:128
	v_cvt_pk_bf16_f32 v3, -v55, s0
	global_store_short v[4:5], v3, off offset:144
	v_cvt_pk_bf16_f32 v3, -v52, s0
	global_store_short v[4:5], v3, off offset:160
	v_cvt_pk_bf16_f32 v3, -v53, s0
	global_store_short v[4:5], v3, off offset:176
	v_cvt_pk_bf16_f32 v3, -v48, s0
	global_store_short v[4:5], v3, off offset:192
	v_cvt_pk_bf16_f32 v3, -v49, s0
	global_store_short v[4:5], v3, off offset:208
	v_cvt_pk_bf16_f32 v3, -v46, s0
	global_store_short v[4:5], v3, off offset:224
	v_cvt_pk_bf16_f32 v3, -v47, s0
	global_store_short v[4:5], v3, off offset:240
	v_add_u32_e32 v4, 0x1000, v32
	v_mov_b32_e32 v5, v2
	v_cvt_pk_bf16_f32 v3, -v42, s0
	v_lshl_add_u64 v[38:39], v[28:29], 0, v[4:5]
	v_ashrrev_i32_e32 v5, 31, v4
	global_store_short v[38:39], v3, off
	v_cvt_pk_bf16_f32 v3, -v43, s0
	v_lshl_add_u64 v[4:5], v[28:29], 0, v[4:5]
	global_store_short v[4:5], v3, off offset:16
	v_cvt_pk_bf16_f32 v3, -v40, s0
	global_store_short v[4:5], v3, off offset:32
	v_cvt_pk_bf16_f32 v3, -v41, s0
	global_store_short v[4:5], v3, off offset:48
	v_cvt_pk_bf16_f32 v3, -v36, s0
	global_store_short v[4:5], v3, off offset:64
	v_cvt_pk_bf16_f32 v3, -v37, s0
	global_store_short v[4:5], v3, off offset:80
	v_cvt_pk_bf16_f32 v3, -v34, s0
	global_store_short v[4:5], v3, off offset:96
	v_cvt_pk_bf16_f32 v3, -v35, s0
	global_store_short v[4:5], v3, off offset:112
	v_cvt_pk_bf16_f32 v3, -v30, s0
	global_store_short v[4:5], v3, off offset:128
	v_cvt_pk_bf16_f32 v3, -v31, s0
	global_store_short v[4:5], v3, off offset:144
	v_cvt_pk_bf16_f32 v3, -v26, s0
	global_store_short v[4:5], v3, off offset:160
	v_cvt_pk_bf16_f32 v3, -v27, s0
	global_store_short v[4:5], v3, off offset:176
	v_cvt_pk_bf16_f32 v3, -v24, s0
	global_store_short v[4:5], v3, off offset:192
	v_cvt_pk_bf16_f32 v3, -v25, s0
	global_store_short v[4:5], v3, off offset:208
	v_cvt_pk_bf16_f32 v3, -v20, s0
	global_store_short v[4:5], v3, off offset:224
	v_cvt_pk_bf16_f32 v3, -v21, s0
	global_store_short v[4:5], v3, off offset:240
	v_add_u32_e32 v4, 0x2000, v32
	v_mov_b32_e32 v5, v2
	v_cvt_pk_bf16_f32 v3, -v18, s0
	v_lshl_add_u64 v[20:21], v[28:29], 0, v[4:5]
	v_ashrrev_i32_e32 v5, 31, v4
	global_store_short v[20:21], v3, off
	v_cvt_pk_bf16_f32 v3, -v19, s0
	v_lshl_add_u64 v[4:5], v[28:29], 0, v[4:5]
	global_store_short v[4:5], v3, off offset:16
	v_cvt_pk_bf16_f32 v3, -v14, s0
	global_store_short v[4:5], v3, off offset:32
	v_cvt_pk_bf16_f32 v3, -v15, s0
	global_store_short v[4:5], v3, off offset:48
	v_cvt_pk_bf16_f32 v3, -v10, s0
	global_store_short v[4:5], v3, off offset:64
	v_cvt_pk_bf16_f32 v3, -v11, s0
	global_store_short v[4:5], v3, off offset:80
	v_cvt_pk_bf16_f32 v3, -v8, s0
	global_store_short v[4:5], v3, off offset:96
	v_cvt_pk_bf16_f32 v3, -v9, s0
	global_store_short v[4:5], v3, off offset:112
	v_cvt_pk_bf16_f32 v3, -v6, s0
	global_store_short v[4:5], v3, off offset:128
	v_cvt_pk_bf16_f32 v3, -v7, s0
	global_store_short v[4:5], v3, off offset:144
	v_cvt_pk_bf16_f32 v3, -v16, s0
	global_store_short v[4:5], v3, off offset:160
	v_cvt_pk_bf16_f32 v3, -v17, s0
	global_store_short v[4:5], v3, off offset:176
	v_cvt_pk_bf16_f32 v3, -v12, s0
	global_store_short v[4:5], v3, off offset:192
	v_cvt_pk_bf16_f32 v3, -v13, s0
	global_store_short v[4:5], v3, off offset:208
	v_cvt_pk_bf16_f32 v3, -v22, s0
	global_store_short v[4:5], v3, off offset:224
	v_cvt_pk_bf16_f32 v3, -v23, s0
	global_store_short v[4:5], v3, off offset:240
